# Epi1 rstd loads hoisted + all P0 transposes hand-written in place (no tail move)
# speedup vs baseline: 1.0031x; 1.0031x over previous
; #define LAS __attribute__((address_space(3)))
; template <int MODE>
; __device__ __forceinline__ void transpose_item(const float* W, int N, bf16_t* WT, int ldt, int coff, LAS float* scr, int item, int lane, const float* g) {
;     const int nblk = N / 32, kb = item / nblk, nb = item % nblk, k0 = 64 * kb, n0 = 32 * nb;
; #pragma unroll 8
;     for (int i = 0; i < 32; ++i) { const int kk = 2 * i + (lane >> 5); float v = W[(size_t)(k0 + kk) * N + n0 + (lane & 31)]; if (MODE >= 1) v *= g[k0 + kk]; scr[kk * 33 + (lane & 31)] = v; }
; __global__ void __launch_bounds__(512, 2) mk_fwd(Args a) {
;     ...
;     if (IN(0)) {
;         constexpr int I_IN = 32 * 320, I_A = 16 * 64, I_O = 32 * 64, I_V = 16 * 32;
;         constexpr int NIT = I_IN + 2 * I_A + I_O + 16 * I_V;
;         for (int it = gw; it < NIT; it += NGW) {
;             int r = it;
;             if (r < I_IN) { transpose_item<2>(a.in[I_WIN], NIN, WIN, DM, 0, scr, r, lane, a.in[I_N1]); continue; } r -= I_IN;
.LBB0_17:
	s_load_dwordx16 s[36:51], s[0:1], 0x0
	s_load_dwordx16 s[52:67], s[0:1], 0x40
	s_lshr_b32 s1, s14, 6
	s_lshl_b32 s0, s2, 3
	s_add_i32 s96, s1, s0
	s_lshl_b32 s80, s3, 3
	s_add_u32 s82, s68, 0x100000
	s_addc_u32 s83, s69, 0
	s_add_u32 s4, s68, 0x2900000
	s_addc_u32 s5, s69, 0
	s_add_u32 s94, s68, 0x3100000
	s_addc_u32 s95, s69, 0
	s_add_u32 s33, s68, 0x18b00000
	s_addc_u32 s14, s69, 0
	s_lshl_b32 s0, s1, 14
	s_add_i32 s6, s0, 0
	v_writelane_b32 v250, s4, 5
	s_cmp_lt_i32 s70, 1
	v_lshlrev_b32_e32 v221, 3, v179
	v_writelane_b32 v250, s5, 6
	s_cselect_b64 s[4:5], -1, 0
	s_cmp_gt_i32 s71, 0
	v_writelane_b32 v250, s1, 7
	s_cselect_b64 s[0:1], -1, 0
	s_and_b64 s[0:1], s[4:5], s[0:1]
	v_bfe_u32 v181, v179, 3, 3
	v_and_b32_e32 v202, 56, v221
	v_and_b32_e32 v201, 31, v179
	v_mul_u32_u24_e32 v0, 0x84, v202
	v_lshlrev_b32_e32 v1, 2, v181
	s_cmpk_lt_i32 s96, 0x4400
	v_lshl_add_u32 v180, v201, 2, s6
	v_add3_u32 v187, s6, v0, v1
	s_cselect_b64 s[6:7], -1, 0
	v_writelane_b32 v250, s6, 8
	v_and_b32_e32 v220, 63, v179
	s_ashr_i32 s81, s80, 31
	v_writelane_b32 v250, s7, 9
	v_bfe_u32 v178, v179, 5, 1
	v_mov_b32_e32 v177, 0
	v_or_b32_e32 v198, 8, v181
	v_or_b32_e32 v199, 16, v181
	v_or_b32_e32 v200, 24, v181
	s_ashr_i32 s97, s96, 31
	v_lshlrev_b32_e32 v176, 3, v220
	s_andn2_b64 vcc, exec, s[0:1]
	v_writelane_b32 v250, s80, 10
	s_nop 1
	v_writelane_b32 v250, s81, 11
	s_cbranch_vccnz .LBB0_71
	s_waitcnt lgkmcnt(0)
	s_and_b32 s0, s96, 7
	s_lshl_b32 s0, s0, 14
	v_readlane_b32 s10, v250, 5
	v_readlane_b32 s11, v250, 6
	s_mov_b32 s72, s33
	s_mov_b32 s73, s14
	s_nop 0
	s_add_u32 s34, s10, 0x800
	s_addc_u32 s35, s11, 0
	s_cmp_lt_u32 s96, 0x2800
	s_cbranch_scc0 .Ltr_done_p0in
	v_lshrrev_b32_e32 v0, 3, v220
	v_and_b32_e32 v1, 7, v220
	v_mul_u32_u24_e32 v2, 0xa000, v0
	v_lshl_add_u32 v36, v1, 4, v2
	v_add_u32_e32 v37, 0x50000, v36
	v_add_u32_e32 v72, 0xa0000, v36
	v_add_u32_e32 v73, 0xf0000, v36
	v_add_u32_e32 v74, 0x140000, v36
	v_add_u32_e32 v75, 0x190000, v36
	v_add_u32_e32 v76, 0x1e0000, v36
	v_add_u32_e32 v182, 0x230000, v36
	v_mul_u32_u24_e32 v2, 0x84, v0
	v_lshl_add_u32 v2, v1, 4, v2
	v_add_u32_e32 v196, s0, v2
	v_mul_u32_u24_e32 v2, 0x420, v1
	v_lshl_add_u32 v2, v0, 2, v2
	v_add_u32_e32 v197, s0, v2
	v_mul_u32_u24_e32 v2, 0x1000, v0
	v_lshl_add_u32 v183, v1, 4, v2
	v_add_u32_e32 v184, 0x8000, v183
	v_add_u32_e32 v185, 0x10000, v183
	v_add_u32_e32 v186, 0x18000, v183
	v_lshlrev_b32_e32 v203, 5, v1
	s_mov_b32 s9, s96
	s_mov_b32 s7, s96
	s_lshr_b32 s15, s7, 6
	s_mul_hi_u32 s15, s15, 0xcccccccd
	s_lshr_b32 s15, s15, 2
	s_mul_i32 s32, s15, 0x140
	s_sub_u32 s32, s7, s32
	s_mul_i32 s84, s15, 0x280000
	s_lshl_b32 s32, s32, 7
	s_add_u32 s84, s84, s32
	s_add_u32 s74, s52, s84
	s_addc_u32 s75, s53, 0
	global_load_dwordx4 v[4:7], v36, s[74:75]
	global_load_dwordx4 v[8:11], v37, s[74:75]
	global_load_dwordx4 v[12:15], v72, s[74:75]
	global_load_dwordx4 v[16:19], v73, s[74:75]
	global_load_dwordx4 v[20:23], v74, s[74:75]
	global_load_dwordx4 v[24:27], v75, s[74:75]
	global_load_dwordx4 v[28:31], v76, s[74:75]
	global_load_dwordx4 v[32:35], v182, s[74:75]
	s_lshl_b32 s84, s15, 8
	s_add_u32 s78, s50, s84
	s_addc_u32 s79, s51, 0
	global_load_dwordx4 v[188:191], v203, s[78:79]
	global_load_dwordx4 v[192:195], v203, s[78:79] offset:16
	s_add_u32 s7, s7, 0x800
	s_cmp_lt_u32 s7, 0x2800
	s_cbranch_scc0 .Ltr_p1_p0in
	s_lshr_b32 s15, s7, 6
	s_mul_hi_u32 s15, s15, 0xcccccccd
	s_lshr_b32 s15, s15, 2
	s_mul_i32 s32, s15, 0x140
	s_sub_u32 s32, s7, s32
	s_mul_i32 s84, s15, 0x280000
	s_lshl_b32 s32, s32, 7
	s_add_u32 s84, s84, s32
	s_add_u32 s74, s52, s84
	s_addc_u32 s75, s53, 0
	global_load_dwordx4 v[40:43], v36, s[74:75]
	global_load_dwordx4 v[44:47], v37, s[74:75]
	global_load_dwordx4 v[48:51], v72, s[74:75]
	global_load_dwordx4 v[52:55], v73, s[74:75]
	global_load_dwordx4 v[56:59], v74, s[74:75]
	global_load_dwordx4 v[60:63], v75, s[74:75]
	global_load_dwordx4 v[64:67], v76, s[74:75]
	global_load_dwordx4 v[68:71], v182, s[74:75]
	s_lshl_b32 s84, s15, 8
	s_add_u32 s78, s50, s84
	s_addc_u32 s79, s51, 0
	global_load_dwordx4 v[224:227], v203, s[78:79]
	global_load_dwordx4 v[228:231], v203, s[78:79] offset:16
.Ltr_p1_p0in:
	s_add_u32 s7, s7, 0x800
.Ltr_st0_p0in:
	s_cmp_lt_u32 s7, 0x2800
	s_cbranch_scc0 .Ltr_nl0_p0in
	s_lshr_b32 s15, s7, 6
	s_mul_hi_u32 s15, s15, 0xcccccccd
	s_lshr_b32 s15, s15, 2
	s_mul_i32 s32, s15, 0x140
	s_sub_u32 s32, s7, s32
	s_mul_i32 s84, s15, 0x280000
	s_lshl_b32 s32, s32, 7
	s_add_u32 s84, s84, s32
	s_add_u32 s74, s52, s84
	s_addc_u32 s75, s53, 0
	global_load_dwordx4 v[96:99], v36, s[74:75]
	global_load_dwordx4 v[100:103], v37, s[74:75]
	global_load_dwordx4 v[104:107], v72, s[74:75]
	global_load_dwordx4 v[108:111], v73, s[74:75]
	global_load_dwordx4 v[112:115], v74, s[74:75]
	global_load_dwordx4 v[116:119], v75, s[74:75]
	global_load_dwordx4 v[120:123], v76, s[74:75]
	global_load_dwordx4 v[124:127], v182, s[74:75]
	s_lshl_b32 s84, s15, 8
	s_add_u32 s78, s50, s84
	s_addc_u32 s79, s51, 0
	global_load_dwordx4 v[232:235], v203, s[78:79]
	global_load_dwordx4 v[236:239], v203, s[78:79] offset:16
	s_waitcnt vmcnt(20)
	s_branch .Ltr_pr0_p0in
.Ltr_nl0_p0in:
	s_sub_u32 s15, s7, 0x800
	s_cmp_lt_u32 s15, 0x2800
	s_cbranch_scc0 .Ltr_w00_p0in
	s_waitcnt vmcnt(10)
	s_branch .Ltr_pr0_p0in

; #define LAS __attribute__((address_space(3)))
; __device__ __forceinline__ unsigned cvtpk(float lo, float hi) { f32x2_t v = {lo, hi}; bf16x2_t b = __builtin_convertvector(v, bf16x2_t); return __builtin_bit_cast(unsigned, b); }
; template <int MODE>
; __device__ __forceinline__ void transpose_item(const float* W, int N, bf16_t* WT, int ldt, int coff, LAS float* scr, int item, int lane, const float* g) {
;     const int nblk = N / 32, kb = item / nblk, nb = item % nblk, k0 = 64 * kb, n0 = 32 * nb;
; #pragma unroll 8
;     for (int i = 0; i < 32; ++i) { const int kk = 2 * i + (lane >> 5); float v = W[(size_t)(k0 + kk) * N + n0 + (lane & 31)]; if (MODE >= 1) v *= g[k0 + kk]; scr[kk * 33 + (lane & 31)] = v; }
;     asm volatile("s_waitcnt lgkmcnt(0)" ::: "memory");
;     const int c = lane & 7;
; #pragma unroll
;     for (int j = 0; j < 4; ++j) {
;         const int n = (lane >> 3) + 8 * j; const LAS float* s = scr + (8 * c) * 33 + n;
;         u32x4 o; o.x = cvtpk(s[0 * 33], s[1 * 33]); o.y = cvtpk(s[2 * 33], s[3 * 33]); o.z = cvtpk(s[4 * 33], s[5 * 33]); o.w = cvtpk(s[6 * 33], s[7 * 33]);
;         int dr = n0 + n;
;         if (MODE == 1) { dr = (dr < DFF) ? 256 * (dr >> 7) + (dr & 127) : 256 * ((dr - DFF) >> 7) + 128 + ((dr - DFF) & 127); }
;         if (MODE == 2) {
;             if (dr >= 6144) { const int t = dr - 6144, ch = t & 2047; dr = 6144 + 256 * (ch >> 7) + ((t >> 11) << 7) + (ch & 127); }
;             else if (dr >= 4096) { const int t = dr - 4096, ch = t & 1023; dr = 4096 + 256 * (ch >> 7) + ((t >> 10) << 7) + (ch & 127); }
;         }
;         *(u32x4*)(WT + (size_t)dr * ldt + coff + k0 + 8 * c) = o;
.Ltr_pr0_p0in:
	s_add_u32 s7, s7, 0x800
	s_lshr_b32 s15, s9, 6
	s_mul_hi_u32 s15, s15, 0xcccccccd
	s_lshr_b32 s15, s15, 2
	s_mul_i32 s32, s15, 0x140
	s_sub_u32 s32, s9, s32
	s_lshl_b32 s32, s32, 5
	s_movk_i32 s84, 0x1000
	s_cmp_ge_u32 s32, 0x1800
	s_cselect_b32 s84, 0x1800, s84
	s_cselect_b32 s85, 11, 10
	s_cmp_lt_u32 s32, 0x1000
	s_cbranch_scc1 .Ltr_m2lin_p0in_0
	s_sub_u32 s32, s32, s84
	s_lshr_b32 s76, s32, s85
	s_lshl_b32 s76, s76, 7
	s_add_u32 s84, s84, s76
	s_bfm_b32 s76, s85, 0
	s_and_b32 s32, s32, s76
	s_and_b32 s76, s32, 0x7f
	s_add_u32 s84, s84, s76
	s_and_b32 s32, s32, 0xffffff80
	s_lshl_b32 s32, s32, 1
	s_add_u32 s32, s84, s32
.Ltr_m2lin_p0in_0:
	s_mul_i32 s84, s32, 0x1000
	s_lshl_b32 s15, s15, 7
	s_add_u32 s84, s84, s15
	s_add_u32 s76, s82, s84
	s_addc_u32 s77, s83, 0
	ds_write_b32 v196, v4 offset:0
	ds_write_b32 v196, v5 offset:4
	ds_write_b32 v196, v6 offset:8
	ds_write_b32 v196, v7 offset:12
	ds_write_b32 v196, v8 offset:1056
	ds_write_b32 v196, v9 offset:1060
	ds_write_b32 v196, v10 offset:1064
	ds_write_b32 v196, v11 offset:1068
	ds_write_b32 v196, v12 offset:2112
	ds_write_b32 v196, v13 offset:2116
	ds_write_b32 v196, v14 offset:2120
	ds_write_b32 v196, v15 offset:2124
	ds_write_b32 v196, v16 offset:3168
	ds_write_b32 v196, v17 offset:3172
	ds_write_b32 v196, v18 offset:3176
	ds_write_b32 v196, v19 offset:3180
	ds_write_b32 v196, v20 offset:4224
	ds_write_b32 v196, v21 offset:4228
	ds_write_b32 v196, v22 offset:4232
	ds_write_b32 v196, v23 offset:4236
	ds_write_b32 v196, v24 offset:5280
	ds_write_b32 v196, v25 offset:5284
	ds_write_b32 v196, v26 offset:5288
	ds_write_b32 v196, v27 offset:5292
	ds_write_b32 v196, v28 offset:6336
	ds_write_b32 v196, v29 offset:6340
	ds_write_b32 v196, v30 offset:6344
	ds_write_b32 v196, v31 offset:6348
	ds_write_b32 v196, v32 offset:7392
	ds_write_b32 v196, v33 offset:7396
	ds_write_b32 v196, v34 offset:7400
	ds_write_b32 v196, v35 offset:7404
	s_waitcnt lgkmcnt(0)
	ds_read2_b32 v[128:129], v197 offset0:0 offset1:8
	ds_read2_b32 v[132:133], v197 offset0:33 offset1:41
	ds_read2_b32 v[136:137], v197 offset0:66 offset1:74
	ds_read2_b32 v[140:141], v197 offset0:99 offset1:107
	ds_read2_b32 v[144:145], v197 offset0:132 offset1:140
	ds_read2_b32 v[148:149], v197 offset0:165 offset1:173
	ds_read2_b32 v[152:153], v197 offset0:198 offset1:206
	ds_read2_b32 v[156:157], v197 offset0:231 offset1:239
	ds_read2_b32 v[130:131], v197 offset0:16 offset1:24
	ds_read2_b32 v[134:135], v197 offset0:49 offset1:57
	ds_read2_b32 v[138:139], v197 offset0:82 offset1:90
	ds_read2_b32 v[142:143], v197 offset0:115 offset1:123
	ds_read2_b32 v[146:147], v197 offset0:148 offset1:156
	ds_read2_b32 v[150:151], v197 offset0:181 offset1:189
	ds_read2_b32 v[154:155], v197 offset0:214 offset1:222
	ds_read2_b32 v[158:159], v197 offset0:247 offset1:255
	s_waitcnt lgkmcnt(0)
	v_mul_f32_e32 v128, v188, v128
	v_mul_f32_e32 v129, v188, v129
	v_mul_f32_e32 v130, v188, v130
	v_mul_f32_e32 v131, v188, v131
	v_mul_f32_e32 v132, v189, v132
	v_mul_f32_e32 v133, v189, v133
	v_mul_f32_e32 v134, v189, v134
	v_mul_f32_e32 v135, v189, v135
	v_mul_f32_e32 v136, v190, v136
	v_mul_f32_e32 v137, v190, v137
	v_mul_f32_e32 v138, v190, v138
	v_mul_f32_e32 v139, v190, v139
	v_mul_f32_e32 v140, v191, v140
	v_mul_f32_e32 v141, v191, v141
	v_mul_f32_e32 v142, v191, v142
	v_mul_f32_e32 v143, v191, v143
	v_mul_f32_e32 v144, v192, v144
	v_mul_f32_e32 v145, v192, v145
	v_mul_f32_e32 v146, v192, v146
	v_mul_f32_e32 v147, v192, v147
	v_mul_f32_e32 v148, v193, v148
	v_mul_f32_e32 v149, v193, v149
	v_mul_f32_e32 v150, v193, v150
	v_mul_f32_e32 v151, v193, v151
	v_mul_f32_e32 v152, v194, v152
	v_mul_f32_e32 v153, v194, v153
	v_mul_f32_e32 v154, v194, v154
	v_mul_f32_e32 v155, v194, v155
	v_mul_f32_e32 v156, v195, v156
	v_mul_f32_e32 v157, v195, v157
	v_mul_f32_e32 v158, v195, v158
	v_mul_f32_e32 v159, v195, v159
	v_cvt_pk_bf16_f32 v204, v128, v132
	v_cvt_pk_bf16_f32 v205, v136, v140
	v_cvt_pk_bf16_f32 v206, v144, v148
	v_cvt_pk_bf16_f32 v207, v152, v156
	global_store_dwordx4 v183, v[204:207], s[76:77]
	v_cvt_pk_bf16_f32 v208, v129, v133
	v_cvt_pk_bf16_f32 v209, v137, v141
	v_cvt_pk_bf16_f32 v210, v145, v149
	v_cvt_pk_bf16_f32 v211, v153, v157
	global_store_dwordx4 v184, v[208:211], s[76:77]
	v_cvt_pk_bf16_f32 v212, v130, v134
	v_cvt_pk_bf16_f32 v213, v138, v142
	v_cvt_pk_bf16_f32 v214, v146, v150
	v_cvt_pk_bf16_f32 v215, v154, v158
	global_store_dwordx4 v185, v[212:215], s[76:77]
	v_cvt_pk_bf16_f32 v216, v131, v135
	v_cvt_pk_bf16_f32 v217, v139, v143
	v_cvt_pk_bf16_f32 v218, v147, v151
	v_cvt_pk_bf16_f32 v219, v155, v159
	global_store_dwordx4 v186, v[216:219], s[76:77]
	s_add_u32 s9, s9, 0x800
	s_cmp_lt_u32 s9, 0x2800
	s_cbranch_scc0 .Ltr_done_p0in
.Ltr_st1_p0in:
	s_cmp_lt_u32 s7, 0x2800
	s_cbranch_scc0 .Ltr_nl1_p0in
	s_lshr_b32 s15, s7, 6
	s_mul_hi_u32 s15, s15, 0xcccccccd
	s_lshr_b32 s15, s15, 2
	s_mul_i32 s32, s15, 0x140
	s_sub_u32 s32, s7, s32
	s_mul_i32 s84, s15, 0x280000
	s_lshl_b32 s32, s32, 7
	s_add_u32 s84, s84, s32
	s_add_u32 s74, s52, s84
	s_addc_u32 s75, s53, 0
	global_load_dwordx4 v[4:7], v36, s[74:75]
	global_load_dwordx4 v[8:11], v37, s[74:75]
	global_load_dwordx4 v[12:15], v72, s[74:75]
	global_load_dwordx4 v[16:19], v73, s[74:75]
	global_load_dwordx4 v[20:23], v74, s[74:75]
	global_load_dwordx4 v[24:27], v75, s[74:75]
	global_load_dwordx4 v[28:31], v76, s[74:75]
	global_load_dwordx4 v[32:35], v182, s[74:75]
	s_lshl_b32 s84, s15, 8
	s_add_u32 s78, s50, s84
	s_addc_u32 s79, s51, 0
	global_load_dwordx4 v[188:191], v203, s[78:79]
	global_load_dwordx4 v[192:195], v203, s[78:79] offset:16
	s_waitcnt vmcnt(20)
	s_branch .Ltr_pr1_p0in

; #define LAS __attribute__((address_space(3)))
; __device__ __forceinline__ unsigned cvtpk(float lo, float hi) { f32x2_t v = {lo, hi}; bf16x2_t b = __builtin_convertvector(v, bf16x2_t); return __builtin_bit_cast(unsigned, b); }
; template <int MODE>
; __device__ __forceinline__ void transpose_item(const float* W, int N, bf16_t* WT, int ldt, int coff, LAS float* scr, int item, int lane, const float* g) {
;     const int nblk = N / 32, kb = item / nblk, nb = item % nblk, k0 = 64 * kb, n0 = 32 * nb;
; #pragma unroll 8
;     for (int i = 0; i < 32; ++i) { const int kk = 2 * i + (lane >> 5); float v = W[(size_t)(k0 + kk) * N + n0 + (lane & 31)]; if (MODE >= 1) v *= g[k0 + kk]; scr[kk * 33 + (lane & 31)] = v; }
;     asm volatile("s_waitcnt lgkmcnt(0)" ::: "memory");
;     const int c = lane & 7;
; #pragma unroll
;     for (int j = 0; j < 4; ++j) {
;         const int n = (lane >> 3) + 8 * j; const LAS float* s = scr + (8 * c) * 33 + n;
;         u32x4 o; o.x = cvtpk(s[0 * 33], s[1 * 33]); o.y = cvtpk(s[2 * 33], s[3 * 33]); o.z = cvtpk(s[4 * 33], s[5 * 33]); o.w = cvtpk(s[6 * 33], s[7 * 33]);
;         int dr = n0 + n;
;         if (MODE == 1) { dr = (dr < DFF) ? 256 * (dr >> 7) + (dr & 127) : 256 * ((dr - DFF) >> 7) + 128 + ((dr - DFF) & 127); }
;         if (MODE == 2) {
;             if (dr >= 6144) { const int t = dr - 6144, ch = t & 2047; dr = 6144 + 256 * (ch >> 7) + ((t >> 11) << 7) + (ch & 127); }
;             else if (dr >= 4096) { const int t = dr - 4096, ch = t & 1023; dr = 4096 + 256 * (ch >> 7) + ((t >> 10) << 7) + (ch & 127); }
;         }
;         *(u32x4*)(WT + (size_t)dr * ldt + coff + k0 + 8 * c) = o;
.Ltr_m2lin_p0in_1:
	s_mul_i32 s84, s32, 0x1000
	s_lshl_b32 s15, s15, 7
	s_add_u32 s84, s84, s15
	s_add_u32 s76, s82, s84
	s_addc_u32 s77, s83, 0
	ds_write_b32 v196, v40 offset:0
	ds_write_b32 v196, v41 offset:4
	ds_write_b32 v196, v42 offset:8
	ds_write_b32 v196, v43 offset:12
	ds_write_b32 v196, v44 offset:1056
	ds_write_b32 v196, v45 offset:1060
	ds_write_b32 v196, v46 offset:1064
	ds_write_b32 v196, v47 offset:1068
	ds_write_b32 v196, v48 offset:2112
	ds_write_b32 v196, v49 offset:2116
	ds_write_b32 v196, v50 offset:2120
	ds_write_b32 v196, v51 offset:2124
	ds_write_b32 v196, v52 offset:3168
	ds_write_b32 v196, v53 offset:3172
	ds_write_b32 v196, v54 offset:3176
	ds_write_b32 v196, v55 offset:3180
	ds_write_b32 v196, v56 offset:4224
	ds_write_b32 v196, v57 offset:4228
	ds_write_b32 v196, v58 offset:4232
	ds_write_b32 v196, v59 offset:4236
	ds_write_b32 v196, v60 offset:5280
	ds_write_b32 v196, v61 offset:5284
	ds_write_b32 v196, v62 offset:5288
	ds_write_b32 v196, v63 offset:5292
	ds_write_b32 v196, v64 offset:6336
	ds_write_b32 v196, v65 offset:6340
	ds_write_b32 v196, v66 offset:6344
	ds_write_b32 v196, v67 offset:6348
	ds_write_b32 v196, v68 offset:7392
	ds_write_b32 v196, v69 offset:7396
	ds_write_b32 v196, v70 offset:7400
	ds_write_b32 v196, v71 offset:7404
	s_waitcnt lgkmcnt(0)
	ds_read2_b32 v[128:129], v197 offset0:0 offset1:8
	ds_read2_b32 v[132:133], v197 offset0:33 offset1:41
	ds_read2_b32 v[136:137], v197 offset0:66 offset1:74
	ds_read2_b32 v[140:141], v197 offset0:99 offset1:107
	ds_read2_b32 v[144:145], v197 offset0:132 offset1:140
	ds_read2_b32 v[148:149], v197 offset0:165 offset1:173
	ds_read2_b32 v[152:153], v197 offset0:198 offset1:206
	ds_read2_b32 v[156:157], v197 offset0:231 offset1:239
	ds_read2_b32 v[130:131], v197 offset0:16 offset1:24
	ds_read2_b32 v[134:135], v197 offset0:49 offset1:57
	ds_read2_b32 v[138:139], v197 offset0:82 offset1:90
	ds_read2_b32 v[142:143], v197 offset0:115 offset1:123
	ds_read2_b32 v[146:147], v197 offset0:148 offset1:156
	ds_read2_b32 v[150:151], v197 offset0:181 offset1:189
	ds_read2_b32 v[154:155], v197 offset0:214 offset1:222
	ds_read2_b32 v[158:159], v197 offset0:247 offset1:255
	s_waitcnt lgkmcnt(0)
	v_mul_f32_e32 v128, v224, v128
	v_mul_f32_e32 v129, v224, v129
	v_mul_f32_e32 v130, v224, v130
	v_mul_f32_e32 v131, v224, v131
	v_mul_f32_e32 v132, v225, v132
	v_mul_f32_e32 v133, v225, v133
	v_mul_f32_e32 v134, v225, v134
	v_mul_f32_e32 v135, v225, v135
	v_mul_f32_e32 v136, v226, v136
	v_mul_f32_e32 v137, v226, v137
	v_mul_f32_e32 v138, v226, v138
	v_mul_f32_e32 v139, v226, v139
	v_mul_f32_e32 v140, v227, v140
	v_mul_f32_e32 v141, v227, v141
	v_mul_f32_e32 v142, v227, v142
	v_mul_f32_e32 v143, v227, v143
	v_mul_f32_e32 v144, v228, v144
	v_mul_f32_e32 v145, v228, v145
	v_mul_f32_e32 v146, v228, v146
	v_mul_f32_e32 v147, v228, v147
	v_mul_f32_e32 v148, v229, v148
	v_mul_f32_e32 v149, v229, v149
	v_mul_f32_e32 v150, v229, v150
	v_mul_f32_e32 v151, v229, v151
	v_mul_f32_e32 v152, v230, v152
	v_mul_f32_e32 v153, v230, v153
	v_mul_f32_e32 v154, v230, v154
	v_mul_f32_e32 v155, v230, v155
	v_mul_f32_e32 v156, v231, v156
	v_mul_f32_e32 v157, v231, v157
	v_mul_f32_e32 v158, v231, v158
	v_mul_f32_e32 v159, v231, v159
	v_cvt_pk_bf16_f32 v204, v128, v132
	v_cvt_pk_bf16_f32 v205, v136, v140
	v_cvt_pk_bf16_f32 v206, v144, v148
	v_cvt_pk_bf16_f32 v207, v152, v156
	global_store_dwordx4 v183, v[204:207], s[76:77]
	v_cvt_pk_bf16_f32 v208, v129, v133
	v_cvt_pk_bf16_f32 v209, v137, v141
	v_cvt_pk_bf16_f32 v210, v145, v149
	v_cvt_pk_bf16_f32 v211, v153, v157
	global_store_dwordx4 v184, v[208:211], s[76:77]
	v_cvt_pk_bf16_f32 v212, v130, v134
	v_cvt_pk_bf16_f32 v213, v138, v142
	v_cvt_pk_bf16_f32 v214, v146, v150
	v_cvt_pk_bf16_f32 v215, v154, v158
	global_store_dwordx4 v185, v[212:215], s[76:77]
	v_cvt_pk_bf16_f32 v216, v131, v135
	v_cvt_pk_bf16_f32 v217, v139, v143
	v_cvt_pk_bf16_f32 v218, v147, v151
	v_cvt_pk_bf16_f32 v219, v155, v159
	global_store_dwordx4 v186, v[216:219], s[76:77]
	s_add_u32 s9, s9, 0x800
	s_cmp_lt_u32 s9, 0x2800
	s_cbranch_scc0 .Ltr_done_p0in
.Ltr_st2_p0in:
	s_cmp_lt_u32 s7, 0x2800
	s_cbranch_scc0 .Ltr_nl2_p0in
	s_lshr_b32 s15, s7, 6
	s_mul_hi_u32 s15, s15, 0xcccccccd
	s_lshr_b32 s15, s15, 2
	s_mul_i32 s32, s15, 0x140
	s_sub_u32 s32, s7, s32
	s_mul_i32 s84, s15, 0x280000
	s_lshl_b32 s32, s32, 7
	s_add_u32 s84, s84, s32
	s_add_u32 s74, s52, s84
	s_addc_u32 s75, s53, 0
	global_load_dwordx4 v[40:43], v36, s[74:75]
	global_load_dwordx4 v[44:47], v37, s[74:75]
	global_load_dwordx4 v[48:51], v72, s[74:75]
	global_load_dwordx4 v[52:55], v73, s[74:75]
	global_load_dwordx4 v[56:59], v74, s[74:75]
	global_load_dwordx4 v[60:63], v75, s[74:75]
	global_load_dwordx4 v[64:67], v76, s[74:75]
	global_load_dwordx4 v[68:71], v182, s[74:75]
	s_lshl_b32 s84, s15, 8
	s_add_u32 s78, s50, s84
	s_addc_u32 s79, s51, 0
	global_load_dwordx4 v[224:227], v203, s[78:79]
	global_load_dwordx4 v[228:231], v203, s[78:79] offset:16
	s_waitcnt vmcnt(20)
	s_branch .Ltr_pr2_p0in

; #define LAS __attribute__((address_space(3)))
; __device__ __forceinline__ unsigned cvtpk(float lo, float hi) { f32x2_t v = {lo, hi}; bf16x2_t b = __builtin_convertvector(v, bf16x2_t); return __builtin_bit_cast(unsigned, b); }
; template <int MODE>
; __device__ __forceinline__ void transpose_item(const float* W, int N, bf16_t* WT, int ldt, int coff, LAS float* scr, int item, int lane, const float* g) {
;     const int nblk = N / 32, kb = item / nblk, nb = item % nblk, k0 = 64 * kb, n0 = 32 * nb;
; #pragma unroll 8
;     for (int i = 0; i < 32; ++i) { const int kk = 2 * i + (lane >> 5); float v = W[(size_t)(k0 + kk) * N + n0 + (lane & 31)]; if (MODE >= 1) v *= g[k0 + kk]; scr[kk * 33 + (lane & 31)] = v; }
;     asm volatile("s_waitcnt lgkmcnt(0)" ::: "memory");
;     const int c = lane & 7;
; #pragma unroll
;     for (int j = 0; j < 4; ++j) {
;         const int n = (lane >> 3) + 8 * j; const LAS float* s = scr + (8 * c) * 33 + n;
;         u32x4 o; o.x = cvtpk(s[0 * 33], s[1 * 33]); o.y = cvtpk(s[2 * 33], s[3 * 33]); o.z = cvtpk(s[4 * 33], s[5 * 33]); o.w = cvtpk(s[6 * 33], s[7 * 33]);
;         int dr = n0 + n;
;         if (MODE == 1) { dr = (dr < DFF) ? 256 * (dr >> 7) + (dr & 127) : 256 * ((dr - DFF) >> 7) + 128 + ((dr - DFF) & 127); }
;         if (MODE == 2) {
;             if (dr >= 6144) { const int t = dr - 6144, ch = t & 2047; dr = 6144 + 256 * (ch >> 7) + ((t >> 11) << 7) + (ch & 127); }
;             else if (dr >= 4096) { const int t = dr - 4096, ch = t & 1023; dr = 4096 + 256 * (ch >> 7) + ((t >> 10) << 7) + (ch & 127); }
;         }
;         *(u32x4*)(WT + (size_t)dr * ldt + coff + k0 + 8 * c) = o;
; __global__ void __launch_bounds__(512, 2) mk_fwd(Args a) {
;     ...
;             if (r < I_A) { transpose_item<0>(a.in[I_WA], DM, WAB, 2048, 0, scr, r, lane, nullptr); continue; } r -= I_A;
.Ltr_m2lin_p0in_2:
	s_mul_i32 s84, s32, 0x1000
	s_lshl_b32 s15, s15, 7
	s_add_u32 s84, s84, s15
	s_add_u32 s76, s82, s84
	s_addc_u32 s77, s83, 0
	ds_write_b32 v196, v96 offset:0
	ds_write_b32 v196, v97 offset:4
	ds_write_b32 v196, v98 offset:8
	ds_write_b32 v196, v99 offset:12
	ds_write_b32 v196, v100 offset:1056
	ds_write_b32 v196, v101 offset:1060
	ds_write_b32 v196, v102 offset:1064
	ds_write_b32 v196, v103 offset:1068
	ds_write_b32 v196, v104 offset:2112
	ds_write_b32 v196, v105 offset:2116
	ds_write_b32 v196, v106 offset:2120
	ds_write_b32 v196, v107 offset:2124
	ds_write_b32 v196, v108 offset:3168
	ds_write_b32 v196, v109 offset:3172
	ds_write_b32 v196, v110 offset:3176
	ds_write_b32 v196, v111 offset:3180
	ds_write_b32 v196, v112 offset:4224
	ds_write_b32 v196, v113 offset:4228
	ds_write_b32 v196, v114 offset:4232
	ds_write_b32 v196, v115 offset:4236
	ds_write_b32 v196, v116 offset:5280
	ds_write_b32 v196, v117 offset:5284
	ds_write_b32 v196, v118 offset:5288
	ds_write_b32 v196, v119 offset:5292
	ds_write_b32 v196, v120 offset:6336
	ds_write_b32 v196, v121 offset:6340
	ds_write_b32 v196, v122 offset:6344
	ds_write_b32 v196, v123 offset:6348
	ds_write_b32 v196, v124 offset:7392
	ds_write_b32 v196, v125 offset:7396
	ds_write_b32 v196, v126 offset:7400
	ds_write_b32 v196, v127 offset:7404
	s_waitcnt lgkmcnt(0)
	ds_read2_b32 v[128:129], v197 offset0:0 offset1:8
	ds_read2_b32 v[132:133], v197 offset0:33 offset1:41
	ds_read2_b32 v[136:137], v197 offset0:66 offset1:74
	ds_read2_b32 v[140:141], v197 offset0:99 offset1:107
	ds_read2_b32 v[144:145], v197 offset0:132 offset1:140
	ds_read2_b32 v[148:149], v197 offset0:165 offset1:173
	ds_read2_b32 v[152:153], v197 offset0:198 offset1:206
	ds_read2_b32 v[156:157], v197 offset0:231 offset1:239
	ds_read2_b32 v[130:131], v197 offset0:16 offset1:24
	ds_read2_b32 v[134:135], v197 offset0:49 offset1:57
	ds_read2_b32 v[138:139], v197 offset0:82 offset1:90
	ds_read2_b32 v[142:143], v197 offset0:115 offset1:123
	ds_read2_b32 v[146:147], v197 offset0:148 offset1:156
	ds_read2_b32 v[150:151], v197 offset0:181 offset1:189
	ds_read2_b32 v[154:155], v197 offset0:214 offset1:222
	ds_read2_b32 v[158:159], v197 offset0:247 offset1:255
	s_waitcnt lgkmcnt(0)
	v_mul_f32_e32 v128, v232, v128
	v_mul_f32_e32 v129, v232, v129
	v_mul_f32_e32 v130, v232, v130
	v_mul_f32_e32 v131, v232, v131
	v_mul_f32_e32 v132, v233, v132
	v_mul_f32_e32 v133, v233, v133
	v_mul_f32_e32 v134, v233, v134
	v_mul_f32_e32 v135, v233, v135
	v_mul_f32_e32 v136, v234, v136
	v_mul_f32_e32 v137, v234, v137
	v_mul_f32_e32 v138, v234, v138
	v_mul_f32_e32 v139, v234, v139
	v_mul_f32_e32 v140, v235, v140
	v_mul_f32_e32 v141, v235, v141
	v_mul_f32_e32 v142, v235, v142
	v_mul_f32_e32 v143, v235, v143
	v_mul_f32_e32 v144, v236, v144
	v_mul_f32_e32 v145, v236, v145
	v_mul_f32_e32 v146, v236, v146
	v_mul_f32_e32 v147, v236, v147
	v_mul_f32_e32 v148, v237, v148
	v_mul_f32_e32 v149, v237, v149
	v_mul_f32_e32 v150, v237, v150
	v_mul_f32_e32 v151, v237, v151
	v_mul_f32_e32 v152, v238, v152
	v_mul_f32_e32 v153, v238, v153
	v_mul_f32_e32 v154, v238, v154
	v_mul_f32_e32 v155, v238, v155
	v_mul_f32_e32 v156, v239, v156
	v_mul_f32_e32 v157, v239, v157
	v_mul_f32_e32 v158, v239, v158
	v_mul_f32_e32 v159, v239, v159
	v_cvt_pk_bf16_f32 v204, v128, v132
	v_cvt_pk_bf16_f32 v205, v136, v140
	v_cvt_pk_bf16_f32 v206, v144, v148
	v_cvt_pk_bf16_f32 v207, v152, v156
	global_store_dwordx4 v183, v[204:207], s[76:77]
	v_cvt_pk_bf16_f32 v208, v129, v133
	v_cvt_pk_bf16_f32 v209, v137, v141
	v_cvt_pk_bf16_f32 v210, v145, v149
	v_cvt_pk_bf16_f32 v211, v153, v157
	global_store_dwordx4 v184, v[208:211], s[76:77]
	v_cvt_pk_bf16_f32 v212, v130, v134
	v_cvt_pk_bf16_f32 v213, v138, v142
	v_cvt_pk_bf16_f32 v214, v146, v150
	v_cvt_pk_bf16_f32 v215, v154, v158
	global_store_dwordx4 v185, v[212:215], s[76:77]
	v_cvt_pk_bf16_f32 v216, v131, v135
	v_cvt_pk_bf16_f32 v217, v139, v143
	v_cvt_pk_bf16_f32 v218, v147, v151
	v_cvt_pk_bf16_f32 v219, v155, v159
	global_store_dwordx4 v186, v[216:219], s[76:77]
	s_add_u32 s9, s9, 0x800
	s_cmp_lt_u32 s9, 0x2800
	s_cbranch_scc0 .Ltr_done_p0in
	s_branch .Ltr_st0_p0in
.Ltr_done_p0in:
	s_cmp_lt_u32 s96, 0x400
	s_cbranch_scc0 .Ltr_done_p0wa
	v_lshrrev_b32_e32 v0, 3, v220
	v_and_b32_e32 v1, 7, v220
	v_mul_u32_u24_e32 v2, 0x2000, v0
	v_lshl_add_u32 v36, v1, 4, v2
	v_add_u32_e32 v37, 0x10000, v36
	v_add_u32_e32 v72, 0x20000, v36
	v_add_u32_e32 v73, 0x30000, v36
	v_add_u32_e32 v74, 0x40000, v36
	v_add_u32_e32 v75, 0x50000, v36
	v_add_u32_e32 v76, 0x60000, v36
	v_add_u32_e32 v182, 0x70000, v36
	v_mul_u32_u24_e32 v2, 0x84, v0
	v_lshl_add_u32 v2, v1, 4, v2
	v_add_u32_e32 v188, s0, v2
	v_mul_u32_u24_e32 v2, 0x420, v1
	v_lshl_add_u32 v2, v0, 2, v2
	v_add_u32_e32 v189, s0, v2
	v_mul_u32_u24_e32 v2, 0x1000, v0
	v_lshl_add_u32 v183, v1, 4, v2
	v_add_u32_e32 v184, 0x8000, v183
	v_add_u32_e32 v185, 0x10000, v183
	v_add_u32_e32 v186, 0x18000, v183
	s_mov_b32 s9, s96
	s_mov_b32 s7, s96
	s_lshr_b32 s15, s7, 6
	s_and_b32 s32, s7, 0x3f
	s_mul_i32 s78, s15, 0x80000
	s_lshl_b32 s32, s32, 7
	s_add_u32 s78, s78, s32
	s_add_u32 s74, s66, s78
	s_addc_u32 s75, s67, 0
	global_load_dwordx4 v[4:7], v36, s[74:75]
	global_load_dwordx4 v[8:11], v37, s[74:75]
	global_load_dwordx4 v[12:15], v72, s[74:75]
	global_load_dwordx4 v[16:19], v73, s[74:75]
	global_load_dwordx4 v[20:23], v74, s[74:75]
	global_load_dwordx4 v[24:27], v75, s[74:75]
	global_load_dwordx4 v[28:31], v76, s[74:75]
	global_load_dwordx4 v[32:35], v182, s[74:75]
	s_add_u32 s7, s7, 0x800
	s_cmp_lt_u32 s7, 0x400
	s_cbranch_scc0 .Ltr_p1_p0wa
	s_lshr_b32 s15, s7, 6
	s_and_b32 s32, s7, 0x3f
	s_mul_i32 s78, s15, 0x80000
	s_lshl_b32 s32, s32, 7
	s_add_u32 s78, s78, s32
	s_add_u32 s74, s66, s78
	s_addc_u32 s75, s67, 0
	global_load_dwordx4 v[40:43], v36, s[74:75]
	global_load_dwordx4 v[44:47], v37, s[74:75]
	global_load_dwordx4 v[48:51], v72, s[74:75]
	global_load_dwordx4 v[52:55], v73, s[74:75]
	global_load_dwordx4 v[56:59], v74, s[74:75]
	global_load_dwordx4 v[60:63], v75, s[74:75]
	global_load_dwordx4 v[64:67], v76, s[74:75]
	global_load_dwordx4 v[68:71], v182, s[74:75]

; #define LAS __attribute__((address_space(3)))
; template <int MODE>
; __device__ __forceinline__ void transpose_item(const float* W, int N, bf16_t* WT, int ldt, int coff, LAS float* scr, int item, int lane, const float* g) {
;     const int nblk = N / 32, kb = item / nblk, nb = item % nblk, k0 = 64 * kb, n0 = 32 * nb;
; #pragma unroll 8
;     for (int i = 0; i < 32; ++i) { const int kk = 2 * i + (lane >> 5); float v = W[(size_t)(k0 + kk) * N + n0 + (lane & 31)]; if (MODE >= 1) v *= g[k0 + kk]; scr[kk * 33 + (lane & 31)] = v; }
; __global__ void __launch_bounds__(512, 2) mk_fwd(Args a) {
;     ...
;             if (r < I_A) { transpose_item<0>(a.in[I_WA], DM, WAB, 2048, 0, scr, r, lane, nullptr); continue; } r -= I_A;
.Ltr_st0_p0wa:
	s_cmp_lt_u32 s7, 0x400
	s_cbranch_scc0 .Ltr_nl0_p0wa
	s_lshr_b32 s15, s7, 6
	s_and_b32 s32, s7, 0x3f
	s_mul_i32 s78, s15, 0x80000
	s_lshl_b32 s32, s32, 7
	s_add_u32 s78, s78, s32
	s_add_u32 s74, s66, s78
	s_addc_u32 s75, s67, 0
	global_load_dwordx4 v[96:99], v36, s[74:75]
	global_load_dwordx4 v[100:103], v37, s[74:75]
	global_load_dwordx4 v[104:107], v72, s[74:75]
	global_load_dwordx4 v[108:111], v73, s[74:75]
	global_load_dwordx4 v[112:115], v74, s[74:75]
	global_load_dwordx4 v[116:119], v75, s[74:75]
	global_load_dwordx4 v[120:123], v76, s[74:75]
	global_load_dwordx4 v[124:127], v182, s[74:75]
	s_waitcnt vmcnt(16)
	s_branch .Ltr_pr0_p0wa
.Ltr_nl0_p0wa:
	s_sub_u32 s15, s7, 0x800
	s_cmp_lt_u32 s15, 0x400
	s_cbranch_scc0 .Ltr_w00_p0wa
	s_waitcnt vmcnt(8)
	s_branch .Ltr_pr0_p0wa

; #define LAS __attribute__((address_space(3)))
; __device__ __forceinline__ unsigned cvtpk(float lo, float hi) { f32x2_t v = {lo, hi}; bf16x2_t b = __builtin_convertvector(v, bf16x2_t); return __builtin_bit_cast(unsigned, b); }
; template <int MODE>
; __device__ __forceinline__ void transpose_item(const float* W, int N, bf16_t* WT, int ldt, int coff, LAS float* scr, int item, int lane, const float* g) {
;     ...
;     for (int i = 0; i < 32; ++i) { const int kk = 2 * i + (lane >> 5); float v = W[(size_t)(k0 + kk) * N + n0 + (lane & 31)]; if (MODE >= 1) v *= g[k0 + kk]; scr[kk * 33 + (lane & 31)] = v; }
;     asm volatile("s_waitcnt lgkmcnt(0)" ::: "memory");
;     const int c = lane & 7;
; #pragma unroll
;     for (int j = 0; j < 4; ++j) {
;         const int n = (lane >> 3) + 8 * j; const LAS float* s = scr + (8 * c) * 33 + n;
;         u32x4 o; o.x = cvtpk(s[0 * 33], s[1 * 33]); o.y = cvtpk(s[2 * 33], s[3 * 33]); o.z = cvtpk(s[4 * 33], s[5 * 33]); o.w = cvtpk(s[6 * 33], s[7 * 33]);
;         int dr = n0 + n;
;         if (MODE == 1) { dr = (dr < DFF) ? 256 * (dr >> 7) + (dr & 127) : 256 * ((dr - DFF) >> 7) + 128 + ((dr - DFF) & 127); }
;         if (MODE == 2) {
;             if (dr >= 6144) { const int t = dr - 6144, ch = t & 2047; dr = 6144 + 256 * (ch >> 7) + ((t >> 11) << 7) + (ch & 127); }
;             else if (dr >= 4096) { const int t = dr - 4096, ch = t & 1023; dr = 4096 + 256 * (ch >> 7) + ((t >> 10) << 7) + (ch & 127); }
;         }
;         *(u32x4*)(WT + (size_t)dr * ldt + coff + k0 + 8 * c) = o;
; __global__ void __launch_bounds__(512, 2) mk_fwd(Args a) {
;     ...
;             if (r < I_A) { transpose_item<0>(a.in[I_WA], DM, WAB, 2048, 0, scr, r, lane, nullptr); continue; } r -= I_A;
.Ltr_pr0_p0wa:
	s_add_u32 s7, s7, 0x800
	s_lshr_b32 s15, s9, 6
	s_and_b32 s32, s9, 0x3f
	s_mul_i32 s78, s32, 0x20000
	s_lshl_b32 s15, s15, 7
	s_add_u32 s78, s78, s15
	s_add_u32 s76, s10, s78
	s_addc_u32 s77, s11, 0
	ds_write_b32 v188, v4 offset:0
	ds_write_b32 v188, v5 offset:4
	ds_write_b32 v188, v6 offset:8
	ds_write_b32 v188, v7 offset:12
	ds_write_b32 v188, v8 offset:1056
	ds_write_b32 v188, v9 offset:1060
	ds_write_b32 v188, v10 offset:1064
	ds_write_b32 v188, v11 offset:1068
	ds_write_b32 v188, v12 offset:2112
	ds_write_b32 v188, v13 offset:2116
	ds_write_b32 v188, v14 offset:2120
	ds_write_b32 v188, v15 offset:2124
	ds_write_b32 v188, v16 offset:3168
	ds_write_b32 v188, v17 offset:3172
	ds_write_b32 v188, v18 offset:3176
	ds_write_b32 v188, v19 offset:3180
	ds_write_b32 v188, v20 offset:4224
	ds_write_b32 v188, v21 offset:4228
	ds_write_b32 v188, v22 offset:4232
	ds_write_b32 v188, v23 offset:4236
	ds_write_b32 v188, v24 offset:5280
	ds_write_b32 v188, v25 offset:5284
	ds_write_b32 v188, v26 offset:5288
	ds_write_b32 v188, v27 offset:5292
	ds_write_b32 v188, v28 offset:6336
	ds_write_b32 v188, v29 offset:6340
	ds_write_b32 v188, v30 offset:6344
	ds_write_b32 v188, v31 offset:6348
	ds_write_b32 v188, v32 offset:7392
	ds_write_b32 v188, v33 offset:7396
	ds_write_b32 v188, v34 offset:7400
	ds_write_b32 v188, v35 offset:7404
	s_waitcnt lgkmcnt(0)
	ds_read2_b32 v[128:129], v189 offset0:0 offset1:8
	ds_read2_b32 v[132:133], v189 offset0:33 offset1:41
	ds_read2_b32 v[136:137], v189 offset0:66 offset1:74
	ds_read2_b32 v[140:141], v189 offset0:99 offset1:107
	ds_read2_b32 v[144:145], v189 offset0:132 offset1:140
	ds_read2_b32 v[148:149], v189 offset0:165 offset1:173
	ds_read2_b32 v[152:153], v189 offset0:198 offset1:206
	ds_read2_b32 v[156:157], v189 offset0:231 offset1:239
	ds_read2_b32 v[130:131], v189 offset0:16 offset1:24
	ds_read2_b32 v[134:135], v189 offset0:49 offset1:57
	ds_read2_b32 v[138:139], v189 offset0:82 offset1:90
	ds_read2_b32 v[142:143], v189 offset0:115 offset1:123
	ds_read2_b32 v[146:147], v189 offset0:148 offset1:156
	ds_read2_b32 v[150:151], v189 offset0:181 offset1:189
	ds_read2_b32 v[154:155], v189 offset0:214 offset1:222
	ds_read2_b32 v[158:159], v189 offset0:247 offset1:255
	s_waitcnt lgkmcnt(0)
	v_cvt_pk_bf16_f32 v204, v128, v132
	v_cvt_pk_bf16_f32 v205, v136, v140
	v_cvt_pk_bf16_f32 v206, v144, v148
	v_cvt_pk_bf16_f32 v207, v152, v156
	global_store_dwordx4 v183, v[204:207], s[76:77]
	v_cvt_pk_bf16_f32 v208, v129, v133
	v_cvt_pk_bf16_f32 v209, v137, v141
	v_cvt_pk_bf16_f32 v210, v145, v149
	v_cvt_pk_bf16_f32 v211, v153, v157
	global_store_dwordx4 v184, v[208:211], s[76:77]
	v_cvt_pk_bf16_f32 v212, v130, v134
	v_cvt_pk_bf16_f32 v213, v138, v142
	v_cvt_pk_bf16_f32 v214, v146, v150
	v_cvt_pk_bf16_f32 v215, v154, v158
	global_store_dwordx4 v185, v[212:215], s[76:77]
	v_cvt_pk_bf16_f32 v216, v131, v135
	v_cvt_pk_bf16_f32 v217, v139, v143
	v_cvt_pk_bf16_f32 v218, v147, v151
	v_cvt_pk_bf16_f32 v219, v155, v159
	global_store_dwordx4 v186, v[216:219], s[76:77]
	s_add_u32 s9, s9, 0x800
	s_cmp_lt_u32 s9, 0x400
	s_cbranch_scc0 .Ltr_done_p0wa
.Ltr_st1_p0wa:
	s_cmp_lt_u32 s7, 0x400
	s_cbranch_scc0 .Ltr_nl1_p0wa
	s_lshr_b32 s15, s7, 6
	s_and_b32 s32, s7, 0x3f
	s_mul_i32 s78, s15, 0x80000
	s_lshl_b32 s32, s32, 7
	s_add_u32 s78, s78, s32
	s_add_u32 s74, s66, s78
	s_addc_u32 s75, s67, 0
	global_load_dwordx4 v[4:7], v36, s[74:75]
	global_load_dwordx4 v[8:11], v37, s[74:75]
	global_load_dwordx4 v[12:15], v72, s[74:75]
	global_load_dwordx4 v[16:19], v73, s[74:75]
	global_load_dwordx4 v[20:23], v74, s[74:75]
	global_load_dwordx4 v[24:27], v75, s[74:75]
	global_load_dwordx4 v[28:31], v76, s[74:75]
	global_load_dwordx4 v[32:35], v182, s[74:75]
	s_waitcnt vmcnt(16)
	s_branch .Ltr_pr1_p0wa

; #define LAS __attribute__((address_space(3)))
; __device__ __forceinline__ unsigned cvtpk(float lo, float hi) { f32x2_t v = {lo, hi}; bf16x2_t b = __builtin_convertvector(v, bf16x2_t); return __builtin_bit_cast(unsigned, b); }
; template <int MODE>
; __device__ __forceinline__ void transpose_item(const float* W, int N, bf16_t* WT, int ldt, int coff, LAS float* scr, int item, int lane, const float* g) {
;     ...
;     for (int i = 0; i < 32; ++i) { const int kk = 2 * i + (lane >> 5); float v = W[(size_t)(k0 + kk) * N + n0 + (lane & 31)]; if (MODE >= 1) v *= g[k0 + kk]; scr[kk * 33 + (lane & 31)] = v; }
;     asm volatile("s_waitcnt lgkmcnt(0)" ::: "memory");
;     const int c = lane & 7;
; #pragma unroll
;     for (int j = 0; j < 4; ++j) {
;         const int n = (lane >> 3) + 8 * j; const LAS float* s = scr + (8 * c) * 33 + n;
;         u32x4 o; o.x = cvtpk(s[0 * 33], s[1 * 33]); o.y = cvtpk(s[2 * 33], s[3 * 33]); o.z = cvtpk(s[4 * 33], s[5 * 33]); o.w = cvtpk(s[6 * 33], s[7 * 33]);
;         int dr = n0 + n;
;         if (MODE == 1) { dr = (dr < DFF) ? 256 * (dr >> 7) + (dr & 127) : 256 * ((dr - DFF) >> 7) + 128 + ((dr - DFF) & 127); }
;         if (MODE == 2) {
;             if (dr >= 6144) { const int t = dr - 6144, ch = t & 2047; dr = 6144 + 256 * (ch >> 7) + ((t >> 11) << 7) + (ch & 127); }
;             else if (dr >= 4096) { const int t = dr - 4096, ch = t & 1023; dr = 4096 + 256 * (ch >> 7) + ((t >> 10) << 7) + (ch & 127); }
;         }
;         *(u32x4*)(WT + (size_t)dr * ldt + coff + k0 + 8 * c) = o;
; __global__ void __launch_bounds__(512, 2) mk_fwd(Args a) {
;     ...
;             if (r < I_A) { transpose_item<0>(a.in[I_WA], DM, WAB, 2048, 0, scr, r, lane, nullptr); continue; } r -= I_A;
.Ltr_pr1_p0wa:
	s_add_u32 s7, s7, 0x800
	s_lshr_b32 s15, s9, 6
	s_and_b32 s32, s9, 0x3f
	s_mul_i32 s78, s32, 0x20000
	s_lshl_b32 s15, s15, 7
	s_add_u32 s78, s78, s15
	s_add_u32 s76, s10, s78
	s_addc_u32 s77, s11, 0
	ds_write_b32 v188, v40 offset:0
	ds_write_b32 v188, v41 offset:4
	ds_write_b32 v188, v42 offset:8
	ds_write_b32 v188, v43 offset:12
	ds_write_b32 v188, v44 offset:1056
	ds_write_b32 v188, v45 offset:1060
	ds_write_b32 v188, v46 offset:1064
	ds_write_b32 v188, v47 offset:1068
	ds_write_b32 v188, v48 offset:2112
	ds_write_b32 v188, v49 offset:2116
	ds_write_b32 v188, v50 offset:2120
	ds_write_b32 v188, v51 offset:2124
	ds_write_b32 v188, v52 offset:3168
	ds_write_b32 v188, v53 offset:3172
	ds_write_b32 v188, v54 offset:3176
	ds_write_b32 v188, v55 offset:3180
	ds_write_b32 v188, v56 offset:4224
	ds_write_b32 v188, v57 offset:4228
	ds_write_b32 v188, v58 offset:4232
	ds_write_b32 v188, v59 offset:4236
	ds_write_b32 v188, v60 offset:5280
	ds_write_b32 v188, v61 offset:5284
	ds_write_b32 v188, v62 offset:5288
	ds_write_b32 v188, v63 offset:5292
	ds_write_b32 v188, v64 offset:6336
	ds_write_b32 v188, v65 offset:6340
	ds_write_b32 v188, v66 offset:6344
	ds_write_b32 v188, v67 offset:6348
	ds_write_b32 v188, v68 offset:7392
	ds_write_b32 v188, v69 offset:7396
	ds_write_b32 v188, v70 offset:7400
	ds_write_b32 v188, v71 offset:7404
	s_waitcnt lgkmcnt(0)
	ds_read2_b32 v[128:129], v189 offset0:0 offset1:8
	ds_read2_b32 v[132:133], v189 offset0:33 offset1:41
	ds_read2_b32 v[136:137], v189 offset0:66 offset1:74
	ds_read2_b32 v[140:141], v189 offset0:99 offset1:107
	ds_read2_b32 v[144:145], v189 offset0:132 offset1:140
	ds_read2_b32 v[148:149], v189 offset0:165 offset1:173
	ds_read2_b32 v[152:153], v189 offset0:198 offset1:206
	ds_read2_b32 v[156:157], v189 offset0:231 offset1:239
	ds_read2_b32 v[130:131], v189 offset0:16 offset1:24
	ds_read2_b32 v[134:135], v189 offset0:49 offset1:57
	ds_read2_b32 v[138:139], v189 offset0:82 offset1:90
	ds_read2_b32 v[142:143], v189 offset0:115 offset1:123
	ds_read2_b32 v[146:147], v189 offset0:148 offset1:156
	ds_read2_b32 v[150:151], v189 offset0:181 offset1:189
	ds_read2_b32 v[154:155], v189 offset0:214 offset1:222
	ds_read2_b32 v[158:159], v189 offset0:247 offset1:255
	s_waitcnt lgkmcnt(0)
	v_cvt_pk_bf16_f32 v204, v128, v132
	v_cvt_pk_bf16_f32 v205, v136, v140
	v_cvt_pk_bf16_f32 v206, v144, v148
	v_cvt_pk_bf16_f32 v207, v152, v156
	global_store_dwordx4 v183, v[204:207], s[76:77]
	v_cvt_pk_bf16_f32 v208, v129, v133
	v_cvt_pk_bf16_f32 v209, v137, v141
	v_cvt_pk_bf16_f32 v210, v145, v149
	v_cvt_pk_bf16_f32 v211, v153, v157
	global_store_dwordx4 v184, v[208:211], s[76:77]
	v_cvt_pk_bf16_f32 v212, v130, v134
	v_cvt_pk_bf16_f32 v213, v138, v142
	v_cvt_pk_bf16_f32 v214, v146, v150
	v_cvt_pk_bf16_f32 v215, v154, v158
	global_store_dwordx4 v185, v[212:215], s[76:77]
	v_cvt_pk_bf16_f32 v216, v131, v135
	v_cvt_pk_bf16_f32 v217, v139, v143
	v_cvt_pk_bf16_f32 v218, v147, v151
	v_cvt_pk_bf16_f32 v219, v155, v159
	global_store_dwordx4 v186, v[216:219], s[76:77]
	s_add_u32 s9, s9, 0x800
	s_cmp_lt_u32 s9, 0x400
	s_cbranch_scc0 .Ltr_done_p0wa
.Ltr_st2_p0wa:
	s_cmp_lt_u32 s7, 0x400
	s_cbranch_scc0 .Ltr_nl2_p0wa
	s_lshr_b32 s15, s7, 6
	s_and_b32 s32, s7, 0x3f
	s_mul_i32 s78, s15, 0x80000
	s_lshl_b32 s32, s32, 7
	s_add_u32 s78, s78, s32
	s_add_u32 s74, s66, s78
	s_addc_u32 s75, s67, 0
	global_load_dwordx4 v[40:43], v36, s[74:75]
	global_load_dwordx4 v[44:47], v37, s[74:75]
	global_load_dwordx4 v[48:51], v72, s[74:75]
	global_load_dwordx4 v[52:55], v73, s[74:75]
	global_load_dwordx4 v[56:59], v74, s[74:75]
	global_load_dwordx4 v[60:63], v75, s[74:75]
	global_load_dwordx4 v[64:67], v76, s[74:75]
	global_load_dwordx4 v[68:71], v182, s[74:75]
	s_waitcnt vmcnt(16)
	s_branch .Ltr_pr2_p0wa

; #define LAS __attribute__((address_space(3)))
; __device__ __forceinline__ unsigned cvtpk(float lo, float hi) { f32x2_t v = {lo, hi}; bf16x2_t b = __builtin_convertvector(v, bf16x2_t); return __builtin_bit_cast(unsigned, b); }
; template <int MODE>
; __device__ __forceinline__ void transpose_item(const float* W, int N, bf16_t* WT, int ldt, int coff, LAS float* scr, int item, int lane, const float* g) {
;     ...
;     for (int i = 0; i < 32; ++i) { const int kk = 2 * i + (lane >> 5); float v = W[(size_t)(k0 + kk) * N + n0 + (lane & 31)]; if (MODE >= 1) v *= g[k0 + kk]; scr[kk * 33 + (lane & 31)] = v; }
;     asm volatile("s_waitcnt lgkmcnt(0)" ::: "memory");
;     const int c = lane & 7;
; #pragma unroll
;     for (int j = 0; j < 4; ++j) {
;         const int n = (lane >> 3) + 8 * j; const LAS float* s = scr + (8 * c) * 33 + n;
;         u32x4 o; o.x = cvtpk(s[0 * 33], s[1 * 33]); o.y = cvtpk(s[2 * 33], s[3 * 33]); o.z = cvtpk(s[4 * 33], s[5 * 33]); o.w = cvtpk(s[6 * 33], s[7 * 33]);
;         int dr = n0 + n;
;         if (MODE == 1) { dr = (dr < DFF) ? 256 * (dr >> 7) + (dr & 127) : 256 * ((dr - DFF) >> 7) + 128 + ((dr - DFF) & 127); }
;         if (MODE == 2) {
;             if (dr >= 6144) { const int t = dr - 6144, ch = t & 2047; dr = 6144 + 256 * (ch >> 7) + ((t >> 11) << 7) + (ch & 127); }
;             else if (dr >= 4096) { const int t = dr - 4096, ch = t & 1023; dr = 4096 + 256 * (ch >> 7) + ((t >> 10) << 7) + (ch & 127); }
;         }
;         *(u32x4*)(WT + (size_t)dr * ldt + coff + k0 + 8 * c) = o;
; __global__ void __launch_bounds__(512, 2) mk_fwd(Args a) {
;     ...
;             if (r < I_A) { transpose_item<0>(a.in[I_WB], DM, WAB, 2048, 1024, scr, r, lane, nullptr); continue; } r -= I_A;
.Ltr_pr2_p0wa:
	s_add_u32 s7, s7, 0x800
	s_lshr_b32 s15, s9, 6
	s_and_b32 s32, s9, 0x3f
	s_mul_i32 s78, s32, 0x20000
	s_lshl_b32 s15, s15, 7
	s_add_u32 s78, s78, s15
	s_add_u32 s76, s10, s78
	s_addc_u32 s77, s11, 0
	ds_write_b32 v188, v96 offset:0
	ds_write_b32 v188, v97 offset:4
	ds_write_b32 v188, v98 offset:8
	ds_write_b32 v188, v99 offset:12
	ds_write_b32 v188, v100 offset:1056
	ds_write_b32 v188, v101 offset:1060
	ds_write_b32 v188, v102 offset:1064
	ds_write_b32 v188, v103 offset:1068
	ds_write_b32 v188, v104 offset:2112
	ds_write_b32 v188, v105 offset:2116
	ds_write_b32 v188, v106 offset:2120
	ds_write_b32 v188, v107 offset:2124
	ds_write_b32 v188, v108 offset:3168
	ds_write_b32 v188, v109 offset:3172
	ds_write_b32 v188, v110 offset:3176
	ds_write_b32 v188, v111 offset:3180
	ds_write_b32 v188, v112 offset:4224
	ds_write_b32 v188, v113 offset:4228
	ds_write_b32 v188, v114 offset:4232
	ds_write_b32 v188, v115 offset:4236
	ds_write_b32 v188, v116 offset:5280
	ds_write_b32 v188, v117 offset:5284
	ds_write_b32 v188, v118 offset:5288
	ds_write_b32 v188, v119 offset:5292
	ds_write_b32 v188, v120 offset:6336
	ds_write_b32 v188, v121 offset:6340
	ds_write_b32 v188, v122 offset:6344
	ds_write_b32 v188, v123 offset:6348
	ds_write_b32 v188, v124 offset:7392
	ds_write_b32 v188, v125 offset:7396
	ds_write_b32 v188, v126 offset:7400
	ds_write_b32 v188, v127 offset:7404
	s_waitcnt lgkmcnt(0)
	ds_read2_b32 v[128:129], v189 offset0:0 offset1:8
	ds_read2_b32 v[132:133], v189 offset0:33 offset1:41
	ds_read2_b32 v[136:137], v189 offset0:66 offset1:74
	ds_read2_b32 v[140:141], v189 offset0:99 offset1:107
	ds_read2_b32 v[144:145], v189 offset0:132 offset1:140
	ds_read2_b32 v[148:149], v189 offset0:165 offset1:173
	ds_read2_b32 v[152:153], v189 offset0:198 offset1:206
	ds_read2_b32 v[156:157], v189 offset0:231 offset1:239
	ds_read2_b32 v[130:131], v189 offset0:16 offset1:24
	ds_read2_b32 v[134:135], v189 offset0:49 offset1:57
	ds_read2_b32 v[138:139], v189 offset0:82 offset1:90
	ds_read2_b32 v[142:143], v189 offset0:115 offset1:123
	ds_read2_b32 v[146:147], v189 offset0:148 offset1:156
	ds_read2_b32 v[150:151], v189 offset0:181 offset1:189
	ds_read2_b32 v[154:155], v189 offset0:214 offset1:222
	ds_read2_b32 v[158:159], v189 offset0:247 offset1:255
	s_waitcnt lgkmcnt(0)
	v_cvt_pk_bf16_f32 v204, v128, v132
	v_cvt_pk_bf16_f32 v205, v136, v140
	v_cvt_pk_bf16_f32 v206, v144, v148
	v_cvt_pk_bf16_f32 v207, v152, v156
	global_store_dwordx4 v183, v[204:207], s[76:77]
	v_cvt_pk_bf16_f32 v208, v129, v133
	v_cvt_pk_bf16_f32 v209, v137, v141
	v_cvt_pk_bf16_f32 v210, v145, v149
	v_cvt_pk_bf16_f32 v211, v153, v157
	global_store_dwordx4 v184, v[208:211], s[76:77]
	v_cvt_pk_bf16_f32 v212, v130, v134
	v_cvt_pk_bf16_f32 v213, v138, v142
	v_cvt_pk_bf16_f32 v214, v146, v150
	v_cvt_pk_bf16_f32 v215, v154, v158
	global_store_dwordx4 v185, v[212:215], s[76:77]
	v_cvt_pk_bf16_f32 v216, v131, v135
	v_cvt_pk_bf16_f32 v217, v139, v143
	v_cvt_pk_bf16_f32 v218, v147, v151
	v_cvt_pk_bf16_f32 v219, v155, v159
	global_store_dwordx4 v186, v[216:219], s[76:77]
	s_add_u32 s9, s9, 0x800
	s_cmp_lt_u32 s9, 0x400
	s_cbranch_scc0 .Ltr_done_p0wa
	s_branch .Ltr_st0_p0wa
.Ltr_done_p0wa:
	s_add_u32 s1, s96, 0x400
	s_and_b32 s1, s1, 0x7ff
	s_cmp_lt_u32 s1, 0x400
	s_cbranch_scc0 .Ltr_done_p0wb
	v_lshrrev_b32_e32 v0, 3, v220
	v_and_b32_e32 v1, 7, v220
	v_mul_u32_u24_e32 v2, 0x2000, v0
	v_lshl_add_u32 v36, v1, 4, v2
	v_add_u32_e32 v37, 0x10000, v36
	v_add_u32_e32 v72, 0x20000, v36
	v_add_u32_e32 v73, 0x30000, v36
	v_add_u32_e32 v74, 0x40000, v36
	v_add_u32_e32 v75, 0x50000, v36
	v_add_u32_e32 v76, 0x60000, v36
	v_add_u32_e32 v182, 0x70000, v36
	v_mul_u32_u24_e32 v2, 0x84, v0
	v_lshl_add_u32 v2, v1, 4, v2
	v_add_u32_e32 v188, s0, v2
	v_mul_u32_u24_e32 v2, 0x420, v1
	v_lshl_add_u32 v2, v0, 2, v2
	v_add_u32_e32 v189, s0, v2
	v_mul_u32_u24_e32 v2, 0x1000, v0
	v_lshl_add_u32 v183, v1, 4, v2
	v_add_u32_e32 v184, 0x8000, v183
	v_add_u32_e32 v185, 0x10000, v183
	v_add_u32_e32 v186, 0x18000, v183
	s_mov_b32 s9, s1
	s_mov_b32 s7, s1
	s_lshr_b32 s15, s7, 6
	s_and_b32 s32, s7, 0x3f
	s_mul_i32 s78, s15, 0x80000
	s_lshl_b32 s32, s32, 7
	s_add_u32 s78, s78, s32
	s_add_u32 s74, s16, s78
	s_addc_u32 s75, s17, 0
	global_load_dwordx4 v[4:7], v36, s[74:75]
	global_load_dwordx4 v[8:11], v37, s[74:75]
	global_load_dwordx4 v[12:15], v72, s[74:75]
	global_load_dwordx4 v[16:19], v73, s[74:75]
	global_load_dwordx4 v[20:23], v74, s[74:75]
	global_load_dwordx4 v[24:27], v75, s[74:75]
	global_load_dwordx4 v[28:31], v76, s[74:75]
	global_load_dwordx4 v[32:35], v182, s[74:75]
	s_add_u32 s7, s7, 0x800
	s_cmp_lt_u32 s7, 0x400
	s_cbranch_scc0 .Ltr_p1_p0wb
	s_lshr_b32 s15, s7, 6
	s_and_b32 s32, s7, 0x3f
	s_mul_i32 s78, s15, 0x80000
	s_lshl_b32 s32, s32, 7
	s_add_u32 s78, s78, s32
	s_add_u32 s74, s16, s78
	s_addc_u32 s75, s17, 0
	global_load_dwordx4 v[40:43], v36, s[74:75]
	global_load_dwordx4 v[44:47], v37, s[74:75]
	global_load_dwordx4 v[48:51], v72, s[74:75]
	global_load_dwordx4 v[52:55], v73, s[74:75]
	global_load_dwordx4 v[56:59], v74, s[74:75]
	global_load_dwordx4 v[60:63], v75, s[74:75]
	global_load_dwordx4 v[64:67], v76, s[74:75]
	global_load_dwordx4 v[68:71], v182, s[74:75]

; #define LAS __attribute__((address_space(3)))
; template <int MODE>
; __device__ __forceinline__ void transpose_item(const float* W, int N, bf16_t* WT, int ldt, int coff, LAS float* scr, int item, int lane, const float* g) {
;     const int nblk = N / 32, kb = item / nblk, nb = item % nblk, k0 = 64 * kb, n0 = 32 * nb;
; #pragma unroll 8
;     for (int i = 0; i < 32; ++i) { const int kk = 2 * i + (lane >> 5); float v = W[(size_t)(k0 + kk) * N + n0 + (lane & 31)]; if (MODE >= 1) v *= g[k0 + kk]; scr[kk * 33 + (lane & 31)] = v; }
; __global__ void __launch_bounds__(512, 2) mk_fwd(Args a) {
;     ...
;             if (r < I_A) { transpose_item<0>(a.in[I_WB], DM, WAB, 2048, 1024, scr, r, lane, nullptr); continue; } r -= I_A;
.Ltr_st0_p0wb:
	s_cmp_lt_u32 s7, 0x400
	s_cbranch_scc0 .Ltr_nl0_p0wb
	s_lshr_b32 s15, s7, 6
	s_and_b32 s32, s7, 0x3f
	s_mul_i32 s78, s15, 0x80000
	s_lshl_b32 s32, s32, 7
	s_add_u32 s78, s78, s32
	s_add_u32 s74, s16, s78
	s_addc_u32 s75, s17, 0
	global_load_dwordx4 v[96:99], v36, s[74:75]
	global_load_dwordx4 v[100:103], v37, s[74:75]
	global_load_dwordx4 v[104:107], v72, s[74:75]
	global_load_dwordx4 v[108:111], v73, s[74:75]
	global_load_dwordx4 v[112:115], v74, s[74:75]
	global_load_dwordx4 v[116:119], v75, s[74:75]
	global_load_dwordx4 v[120:123], v76, s[74:75]
	global_load_dwordx4 v[124:127], v182, s[74:75]
	s_waitcnt vmcnt(16)
	s_branch .Ltr_pr0_p0wb

; #define LAS __attribute__((address_space(3)))
; __device__ __forceinline__ unsigned cvtpk(float lo, float hi) { f32x2_t v = {lo, hi}; bf16x2_t b = __builtin_convertvector(v, bf16x2_t); return __builtin_bit_cast(unsigned, b); }
; template <int MODE>
; __device__ __forceinline__ void transpose_item(const float* W, int N, bf16_t* WT, int ldt, int coff, LAS float* scr, int item, int lane, const float* g) {
;     ...
;     for (int i = 0; i < 32; ++i) { const int kk = 2 * i + (lane >> 5); float v = W[(size_t)(k0 + kk) * N + n0 + (lane & 31)]; if (MODE >= 1) v *= g[k0 + kk]; scr[kk * 33 + (lane & 31)] = v; }
;     asm volatile("s_waitcnt lgkmcnt(0)" ::: "memory");
;     const int c = lane & 7;
; #pragma unroll
;     for (int j = 0; j < 4; ++j) {
;         const int n = (lane >> 3) + 8 * j; const LAS float* s = scr + (8 * c) * 33 + n;
;         u32x4 o; o.x = cvtpk(s[0 * 33], s[1 * 33]); o.y = cvtpk(s[2 * 33], s[3 * 33]); o.z = cvtpk(s[4 * 33], s[5 * 33]); o.w = cvtpk(s[6 * 33], s[7 * 33]);
;         int dr = n0 + n;
;         if (MODE == 1) { dr = (dr < DFF) ? 256 * (dr >> 7) + (dr & 127) : 256 * ((dr - DFF) >> 7) + 128 + ((dr - DFF) & 127); }
;         if (MODE == 2) {
;             if (dr >= 6144) { const int t = dr - 6144, ch = t & 2047; dr = 6144 + 256 * (ch >> 7) + ((t >> 11) << 7) + (ch & 127); }
;             else if (dr >= 4096) { const int t = dr - 4096, ch = t & 1023; dr = 4096 + 256 * (ch >> 7) + ((t >> 10) << 7) + (ch & 127); }
;         }
;         *(u32x4*)(WT + (size_t)dr * ldt + coff + k0 + 8 * c) = o;
; __global__ void __launch_bounds__(512, 2) mk_fwd(Args a) {
;     ...
;             if (r < I_A) { transpose_item<0>(a.in[I_WB], DM, WAB, 2048, 1024, scr, r, lane, nullptr); continue; } r -= I_A;
.Ltr_pr0_p0wb:
	s_add_u32 s7, s7, 0x800
	s_lshr_b32 s15, s9, 6
	s_and_b32 s32, s9, 0x3f
	s_mul_i32 s78, s32, 0x20000
	s_lshl_b32 s15, s15, 7
	s_add_u32 s78, s78, s15
	s_add_u32 s76, s34, s78
	s_addc_u32 s77, s35, 0
	ds_write_b32 v188, v4 offset:0
	ds_write_b32 v188, v5 offset:4
	ds_write_b32 v188, v6 offset:8
	ds_write_b32 v188, v7 offset:12
	ds_write_b32 v188, v8 offset:1056
	ds_write_b32 v188, v9 offset:1060
	ds_write_b32 v188, v10 offset:1064
	ds_write_b32 v188, v11 offset:1068
	ds_write_b32 v188, v12 offset:2112
	ds_write_b32 v188, v13 offset:2116
	ds_write_b32 v188, v14 offset:2120
	ds_write_b32 v188, v15 offset:2124
	ds_write_b32 v188, v16 offset:3168
	ds_write_b32 v188, v17 offset:3172
	ds_write_b32 v188, v18 offset:3176
	ds_write_b32 v188, v19 offset:3180
	ds_write_b32 v188, v20 offset:4224
	ds_write_b32 v188, v21 offset:4228
	ds_write_b32 v188, v22 offset:4232
	ds_write_b32 v188, v23 offset:4236
	ds_write_b32 v188, v24 offset:5280
	ds_write_b32 v188, v25 offset:5284
	ds_write_b32 v188, v26 offset:5288
	ds_write_b32 v188, v27 offset:5292
	ds_write_b32 v188, v28 offset:6336
	ds_write_b32 v188, v29 offset:6340
	ds_write_b32 v188, v30 offset:6344
	ds_write_b32 v188, v31 offset:6348
	ds_write_b32 v188, v32 offset:7392
	ds_write_b32 v188, v33 offset:7396
	ds_write_b32 v188, v34 offset:7400
	ds_write_b32 v188, v35 offset:7404
	s_waitcnt lgkmcnt(0)
	ds_read2_b32 v[128:129], v189 offset0:0 offset1:8
	ds_read2_b32 v[132:133], v189 offset0:33 offset1:41
	ds_read2_b32 v[136:137], v189 offset0:66 offset1:74
	ds_read2_b32 v[140:141], v189 offset0:99 offset1:107
	ds_read2_b32 v[144:145], v189 offset0:132 offset1:140
	ds_read2_b32 v[148:149], v189 offset0:165 offset1:173
	ds_read2_b32 v[152:153], v189 offset0:198 offset1:206
	ds_read2_b32 v[156:157], v189 offset0:231 offset1:239
	ds_read2_b32 v[130:131], v189 offset0:16 offset1:24
	ds_read2_b32 v[134:135], v189 offset0:49 offset1:57
	ds_read2_b32 v[138:139], v189 offset0:82 offset1:90
	ds_read2_b32 v[142:143], v189 offset0:115 offset1:123
	ds_read2_b32 v[146:147], v189 offset0:148 offset1:156
	ds_read2_b32 v[150:151], v189 offset0:181 offset1:189
	ds_read2_b32 v[154:155], v189 offset0:214 offset1:222
	ds_read2_b32 v[158:159], v189 offset0:247 offset1:255
	s_waitcnt lgkmcnt(0)
	v_cvt_pk_bf16_f32 v204, v128, v132
	v_cvt_pk_bf16_f32 v205, v136, v140
	v_cvt_pk_bf16_f32 v206, v144, v148
	v_cvt_pk_bf16_f32 v207, v152, v156
	global_store_dwordx4 v183, v[204:207], s[76:77]
	v_cvt_pk_bf16_f32 v208, v129, v133
	v_cvt_pk_bf16_f32 v209, v137, v141
	v_cvt_pk_bf16_f32 v210, v145, v149
	v_cvt_pk_bf16_f32 v211, v153, v157
	global_store_dwordx4 v184, v[208:211], s[76:77]
	v_cvt_pk_bf16_f32 v212, v130, v134
	v_cvt_pk_bf16_f32 v213, v138, v142
	v_cvt_pk_bf16_f32 v214, v146, v150
	v_cvt_pk_bf16_f32 v215, v154, v158
	global_store_dwordx4 v185, v[212:215], s[76:77]
	v_cvt_pk_bf16_f32 v216, v131, v135
	v_cvt_pk_bf16_f32 v217, v139, v143
	v_cvt_pk_bf16_f32 v218, v147, v151
	v_cvt_pk_bf16_f32 v219, v155, v159
	global_store_dwordx4 v186, v[216:219], s[76:77]
	s_add_u32 s9, s9, 0x800
	s_cmp_lt_u32 s9, 0x400
	s_cbranch_scc0 .Ltr_done_p0wb
.Ltr_st1_p0wb:
	s_cmp_lt_u32 s7, 0x400
	s_cbranch_scc0 .Ltr_nl1_p0wb
	s_lshr_b32 s15, s7, 6
	s_and_b32 s32, s7, 0x3f
	s_mul_i32 s78, s15, 0x80000
	s_lshl_b32 s32, s32, 7
	s_add_u32 s78, s78, s32
	s_add_u32 s74, s16, s78
	s_addc_u32 s75, s17, 0
	global_load_dwordx4 v[4:7], v36, s[74:75]
	global_load_dwordx4 v[8:11], v37, s[74:75]
	global_load_dwordx4 v[12:15], v72, s[74:75]
	global_load_dwordx4 v[16:19], v73, s[74:75]
	global_load_dwordx4 v[20:23], v74, s[74:75]
	global_load_dwordx4 v[24:27], v75, s[74:75]
	global_load_dwordx4 v[28:31], v76, s[74:75]
	global_load_dwordx4 v[32:35], v182, s[74:75]
	s_waitcnt vmcnt(16)
	s_branch .Ltr_pr1_p0wb

; #define LAS __attribute__((address_space(3)))
; __device__ __forceinline__ unsigned cvtpk(float lo, float hi) { f32x2_t v = {lo, hi}; bf16x2_t b = __builtin_convertvector(v, bf16x2_t); return __builtin_bit_cast(unsigned, b); }
; template <int MODE>
; __device__ __forceinline__ void transpose_item(const float* W, int N, bf16_t* WT, int ldt, int coff, LAS float* scr, int item, int lane, const float* g) {
;     ...
;     for (int i = 0; i < 32; ++i) { const int kk = 2 * i + (lane >> 5); float v = W[(size_t)(k0 + kk) * N + n0 + (lane & 31)]; if (MODE >= 1) v *= g[k0 + kk]; scr[kk * 33 + (lane & 31)] = v; }
;     asm volatile("s_waitcnt lgkmcnt(0)" ::: "memory");
;     const int c = lane & 7;
; #pragma unroll
;     for (int j = 0; j < 4; ++j) {
;         const int n = (lane >> 3) + 8 * j; const LAS float* s = scr + (8 * c) * 33 + n;
;         u32x4 o; o.x = cvtpk(s[0 * 33], s[1 * 33]); o.y = cvtpk(s[2 * 33], s[3 * 33]); o.z = cvtpk(s[4 * 33], s[5 * 33]); o.w = cvtpk(s[6 * 33], s[7 * 33]);
;         int dr = n0 + n;
;         if (MODE == 1) { dr = (dr < DFF) ? 256 * (dr >> 7) + (dr & 127) : 256 * ((dr - DFF) >> 7) + 128 + ((dr - DFF) & 127); }
;         if (MODE == 2) {
;             if (dr >= 6144) { const int t = dr - 6144, ch = t & 2047; dr = 6144 + 256 * (ch >> 7) + ((t >> 11) << 7) + (ch & 127); }
;             else if (dr >= 4096) { const int t = dr - 4096, ch = t & 1023; dr = 4096 + 256 * (ch >> 7) + ((t >> 10) << 7) + (ch & 127); }
;         }
;         *(u32x4*)(WT + (size_t)dr * ldt + coff + k0 + 8 * c) = o;
; __global__ void __launch_bounds__(512, 2) mk_fwd(Args a) {
;     ...
;             if (r < I_A) { transpose_item<0>(a.in[I_WB], DM, WAB, 2048, 1024, scr, r, lane, nullptr); continue; } r -= I_A;
.Ltr_pr1_p0wb:
	s_add_u32 s7, s7, 0x800
	s_lshr_b32 s15, s9, 6
	s_and_b32 s32, s9, 0x3f
	s_mul_i32 s78, s32, 0x20000
	s_lshl_b32 s15, s15, 7
	s_add_u32 s78, s78, s15
	s_add_u32 s76, s34, s78
	s_addc_u32 s77, s35, 0
	ds_write_b32 v188, v40 offset:0
	ds_write_b32 v188, v41 offset:4
	ds_write_b32 v188, v42 offset:8
	ds_write_b32 v188, v43 offset:12
	ds_write_b32 v188, v44 offset:1056
	ds_write_b32 v188, v45 offset:1060
	ds_write_b32 v188, v46 offset:1064
	ds_write_b32 v188, v47 offset:1068
	ds_write_b32 v188, v48 offset:2112
	ds_write_b32 v188, v49 offset:2116
	ds_write_b32 v188, v50 offset:2120
	ds_write_b32 v188, v51 offset:2124
	ds_write_b32 v188, v52 offset:3168
	ds_write_b32 v188, v53 offset:3172
	ds_write_b32 v188, v54 offset:3176
	ds_write_b32 v188, v55 offset:3180
	ds_write_b32 v188, v56 offset:4224
	ds_write_b32 v188, v57 offset:4228
	ds_write_b32 v188, v58 offset:4232
	ds_write_b32 v188, v59 offset:4236
	ds_write_b32 v188, v60 offset:5280
	ds_write_b32 v188, v61 offset:5284
	ds_write_b32 v188, v62 offset:5288
	ds_write_b32 v188, v63 offset:5292
	ds_write_b32 v188, v64 offset:6336
	ds_write_b32 v188, v65 offset:6340
	ds_write_b32 v188, v66 offset:6344
	ds_write_b32 v188, v67 offset:6348
	ds_write_b32 v188, v68 offset:7392
	ds_write_b32 v188, v69 offset:7396
	ds_write_b32 v188, v70 offset:7400
	ds_write_b32 v188, v71 offset:7404
	s_waitcnt lgkmcnt(0)
	ds_read2_b32 v[128:129], v189 offset0:0 offset1:8
	ds_read2_b32 v[132:133], v189 offset0:33 offset1:41
	ds_read2_b32 v[136:137], v189 offset0:66 offset1:74
	ds_read2_b32 v[140:141], v189 offset0:99 offset1:107
	ds_read2_b32 v[144:145], v189 offset0:132 offset1:140
	ds_read2_b32 v[148:149], v189 offset0:165 offset1:173
	ds_read2_b32 v[152:153], v189 offset0:198 offset1:206
	ds_read2_b32 v[156:157], v189 offset0:231 offset1:239
	ds_read2_b32 v[130:131], v189 offset0:16 offset1:24
	ds_read2_b32 v[134:135], v189 offset0:49 offset1:57
	ds_read2_b32 v[138:139], v189 offset0:82 offset1:90
	ds_read2_b32 v[142:143], v189 offset0:115 offset1:123
	ds_read2_b32 v[146:147], v189 offset0:148 offset1:156
	ds_read2_b32 v[150:151], v189 offset0:181 offset1:189
	ds_read2_b32 v[154:155], v189 offset0:214 offset1:222
	ds_read2_b32 v[158:159], v189 offset0:247 offset1:255
	s_waitcnt lgkmcnt(0)
	v_cvt_pk_bf16_f32 v204, v128, v132
	v_cvt_pk_bf16_f32 v205, v136, v140
	v_cvt_pk_bf16_f32 v206, v144, v148
	v_cvt_pk_bf16_f32 v207, v152, v156
	global_store_dwordx4 v183, v[204:207], s[76:77]
	v_cvt_pk_bf16_f32 v208, v129, v133
	v_cvt_pk_bf16_f32 v209, v137, v141
	v_cvt_pk_bf16_f32 v210, v145, v149
	v_cvt_pk_bf16_f32 v211, v153, v157
	global_store_dwordx4 v184, v[208:211], s[76:77]
	v_cvt_pk_bf16_f32 v212, v130, v134
	v_cvt_pk_bf16_f32 v213, v138, v142
	v_cvt_pk_bf16_f32 v214, v146, v150
	v_cvt_pk_bf16_f32 v215, v154, v158
	global_store_dwordx4 v185, v[212:215], s[76:77]
	v_cvt_pk_bf16_f32 v216, v131, v135
	v_cvt_pk_bf16_f32 v217, v139, v143
	v_cvt_pk_bf16_f32 v218, v147, v151
	v_cvt_pk_bf16_f32 v219, v155, v159
	global_store_dwordx4 v186, v[216:219], s[76:77]
	s_add_u32 s9, s9, 0x800
	s_cmp_lt_u32 s9, 0x400
	s_cbranch_scc0 .Ltr_done_p0wb
.Ltr_st2_p0wb:
	s_cmp_lt_u32 s7, 0x400
	s_cbranch_scc0 .Ltr_nl2_p0wb
	s_lshr_b32 s15, s7, 6
	s_and_b32 s32, s7, 0x3f
	s_mul_i32 s78, s15, 0x80000
	s_lshl_b32 s32, s32, 7
	s_add_u32 s78, s78, s32
	s_add_u32 s74, s16, s78
	s_addc_u32 s75, s17, 0
	global_load_dwordx4 v[40:43], v36, s[74:75]
	global_load_dwordx4 v[44:47], v37, s[74:75]
	global_load_dwordx4 v[48:51], v72, s[74:75]
	global_load_dwordx4 v[52:55], v73, s[74:75]
	global_load_dwordx4 v[56:59], v74, s[74:75]
	global_load_dwordx4 v[60:63], v75, s[74:75]
	global_load_dwordx4 v[64:67], v76, s[74:75]
	global_load_dwordx4 v[68:71], v182, s[74:75]
	s_waitcnt vmcnt(16)
	s_branch .Ltr_pr2_p0wb

; #define LAS __attribute__((address_space(3)))
; __device__ __forceinline__ unsigned cvtpk(float lo, float hi) { f32x2_t v = {lo, hi}; bf16x2_t b = __builtin_convertvector(v, bf16x2_t); return __builtin_bit_cast(unsigned, b); }
; template <int MODE>
; __device__ __forceinline__ void transpose_item(const float* W, int N, bf16_t* WT, int ldt, int coff, LAS float* scr, int item, int lane, const float* g) {
;     ...
;     for (int i = 0; i < 32; ++i) { const int kk = 2 * i + (lane >> 5); float v = W[(size_t)(k0 + kk) * N + n0 + (lane & 31)]; if (MODE >= 1) v *= g[k0 + kk]; scr[kk * 33 + (lane & 31)] = v; }
;     asm volatile("s_waitcnt lgkmcnt(0)" ::: "memory");
;     const int c = lane & 7;
; #pragma unroll
;     for (int j = 0; j < 4; ++j) {
;         const int n = (lane >> 3) + 8 * j; const LAS float* s = scr + (8 * c) * 33 + n;
;         u32x4 o; o.x = cvtpk(s[0 * 33], s[1 * 33]); o.y = cvtpk(s[2 * 33], s[3 * 33]); o.z = cvtpk(s[4 * 33], s[5 * 33]); o.w = cvtpk(s[6 * 33], s[7 * 33]);
;         int dr = n0 + n;
;         if (MODE == 1) { dr = (dr < DFF) ? 256 * (dr >> 7) + (dr & 127) : 256 * ((dr - DFF) >> 7) + 128 + ((dr - DFF) & 127); }
;         if (MODE == 2) {
;             if (dr >= 6144) { const int t = dr - 6144, ch = t & 2047; dr = 6144 + 256 * (ch >> 7) + ((t >> 11) << 7) + (ch & 127); }
;             else if (dr >= 4096) { const int t = dr - 4096, ch = t & 1023; dr = 4096 + 256 * (ch >> 7) + ((t >> 10) << 7) + (ch & 127); }
;         }
;         *(u32x4*)(WT + (size_t)dr * ldt + coff + k0 + 8 * c) = o;
; __global__ void __launch_bounds__(512, 2) mk_fwd(Args a) {
;     ...
;             if (r < I_O) { transpose_item<0>(a.in[I_WO], DM, WO, DM, 0, scr, r, lane, nullptr); continue; } r -= I_O;
.Ltr_pr2_p0wb:
	s_add_u32 s7, s7, 0x800
	s_lshr_b32 s15, s9, 6
	s_and_b32 s32, s9, 0x3f
	s_mul_i32 s78, s32, 0x20000
	s_lshl_b32 s15, s15, 7
	s_add_u32 s78, s78, s15
	s_add_u32 s76, s34, s78
	s_addc_u32 s77, s35, 0
	ds_write_b32 v188, v96 offset:0
	ds_write_b32 v188, v97 offset:4
	ds_write_b32 v188, v98 offset:8
	ds_write_b32 v188, v99 offset:12
	ds_write_b32 v188, v100 offset:1056
	ds_write_b32 v188, v101 offset:1060
	ds_write_b32 v188, v102 offset:1064
	ds_write_b32 v188, v103 offset:1068
	ds_write_b32 v188, v104 offset:2112
	ds_write_b32 v188, v105 offset:2116
	ds_write_b32 v188, v106 offset:2120
	ds_write_b32 v188, v107 offset:2124
	ds_write_b32 v188, v108 offset:3168
	ds_write_b32 v188, v109 offset:3172
	ds_write_b32 v188, v110 offset:3176
	ds_write_b32 v188, v111 offset:3180
	ds_write_b32 v188, v112 offset:4224
	ds_write_b32 v188, v113 offset:4228
	ds_write_b32 v188, v114 offset:4232
	ds_write_b32 v188, v115 offset:4236
	ds_write_b32 v188, v116 offset:5280
	ds_write_b32 v188, v117 offset:5284
	ds_write_b32 v188, v118 offset:5288
	ds_write_b32 v188, v119 offset:5292
	ds_write_b32 v188, v120 offset:6336
	ds_write_b32 v188, v121 offset:6340
	ds_write_b32 v188, v122 offset:6344
	ds_write_b32 v188, v123 offset:6348
	ds_write_b32 v188, v124 offset:7392
	ds_write_b32 v188, v125 offset:7396
	ds_write_b32 v188, v126 offset:7400
	ds_write_b32 v188, v127 offset:7404
	s_waitcnt lgkmcnt(0)
	ds_read2_b32 v[128:129], v189 offset0:0 offset1:8
	ds_read2_b32 v[132:133], v189 offset0:33 offset1:41
	ds_read2_b32 v[136:137], v189 offset0:66 offset1:74
	ds_read2_b32 v[140:141], v189 offset0:99 offset1:107
	ds_read2_b32 v[144:145], v189 offset0:132 offset1:140
	ds_read2_b32 v[148:149], v189 offset0:165 offset1:173
	ds_read2_b32 v[152:153], v189 offset0:198 offset1:206
	ds_read2_b32 v[156:157], v189 offset0:231 offset1:239
	ds_read2_b32 v[130:131], v189 offset0:16 offset1:24
	ds_read2_b32 v[134:135], v189 offset0:49 offset1:57
	ds_read2_b32 v[138:139], v189 offset0:82 offset1:90
	ds_read2_b32 v[142:143], v189 offset0:115 offset1:123
	ds_read2_b32 v[146:147], v189 offset0:148 offset1:156
	ds_read2_b32 v[150:151], v189 offset0:181 offset1:189
	ds_read2_b32 v[154:155], v189 offset0:214 offset1:222
	ds_read2_b32 v[158:159], v189 offset0:247 offset1:255
	s_waitcnt lgkmcnt(0)
	v_cvt_pk_bf16_f32 v204, v128, v132
	v_cvt_pk_bf16_f32 v205, v136, v140
	v_cvt_pk_bf16_f32 v206, v144, v148
	v_cvt_pk_bf16_f32 v207, v152, v156
	global_store_dwordx4 v183, v[204:207], s[76:77]
	v_cvt_pk_bf16_f32 v208, v129, v133
	v_cvt_pk_bf16_f32 v209, v137, v141
	v_cvt_pk_bf16_f32 v210, v145, v149
	v_cvt_pk_bf16_f32 v211, v153, v157
	global_store_dwordx4 v184, v[208:211], s[76:77]
	v_cvt_pk_bf16_f32 v212, v130, v134
	v_cvt_pk_bf16_f32 v213, v138, v142
	v_cvt_pk_bf16_f32 v214, v146, v150
	v_cvt_pk_bf16_f32 v215, v154, v158
	global_store_dwordx4 v185, v[212:215], s[76:77]
	v_cvt_pk_bf16_f32 v216, v131, v135
	v_cvt_pk_bf16_f32 v217, v139, v143
	v_cvt_pk_bf16_f32 v218, v147, v151
	v_cvt_pk_bf16_f32 v219, v155, v159
	global_store_dwordx4 v186, v[216:219], s[76:77]
	s_add_u32 s9, s9, 0x800
	s_cmp_lt_u32 s9, 0x400
	s_cbranch_scc0 .Ltr_done_p0wb
	s_branch .Ltr_st0_p0wb
.Ltr_done_p0wb:
	s_cmp_lt_u32 s96, 0x800
	s_cbranch_scc0 .Ltr_done_p0wo
	v_lshrrev_b32_e32 v0, 3, v220
	v_and_b32_e32 v1, 7, v220
	v_mul_u32_u24_e32 v2, 0x2000, v0
	v_lshl_add_u32 v36, v1, 4, v2
	v_add_u32_e32 v37, 0x10000, v36
	v_add_u32_e32 v72, 0x20000, v36
	v_add_u32_e32 v73, 0x30000, v36
	v_add_u32_e32 v74, 0x40000, v36
	v_add_u32_e32 v75, 0x50000, v36
	v_add_u32_e32 v76, 0x60000, v36
	v_add_u32_e32 v182, 0x70000, v36
	v_mul_u32_u24_e32 v2, 0x84, v0
	v_lshl_add_u32 v2, v1, 4, v2
	v_add_u32_e32 v188, s0, v2
	v_mul_u32_u24_e32 v2, 0x420, v1
	v_lshl_add_u32 v2, v0, 2, v2
	v_add_u32_e32 v189, s0, v2
	v_mul_u32_u24_e32 v2, 0x1000, v0
	v_lshl_add_u32 v183, v1, 4, v2
	v_add_u32_e32 v184, 0x8000, v183
	v_add_u32_e32 v185, 0x10000, v183
	v_add_u32_e32 v186, 0x18000, v183
	s_mov_b32 s9, s96
	s_mov_b32 s7, s96
	s_lshr_b32 s15, s7, 6
	s_and_b32 s32, s7, 0x3f
	s_mul_i32 s78, s15, 0x80000
	s_lshl_b32 s32, s32, 7
	s_add_u32 s78, s78, s32
	s_add_u32 s74, s18, s78
	s_addc_u32 s75, s19, 0
	global_load_dwordx4 v[4:7], v36, s[74:75]
	global_load_dwordx4 v[8:11], v37, s[74:75]
	global_load_dwordx4 v[12:15], v72, s[74:75]
	global_load_dwordx4 v[16:19], v73, s[74:75]
	global_load_dwordx4 v[20:23], v74, s[74:75]
	global_load_dwordx4 v[24:27], v75, s[74:75]
	global_load_dwordx4 v[28:31], v76, s[74:75]
	global_load_dwordx4 v[32:35], v182, s[74:75]
	s_add_u32 s7, s7, 0x800
	s_cmp_lt_u32 s7, 0x800
	s_cbranch_scc0 .Ltr_p1_p0wo
	s_lshr_b32 s15, s7, 6
	s_and_b32 s32, s7, 0x3f
	s_mul_i32 s78, s15, 0x80000
	s_lshl_b32 s32, s32, 7
	s_add_u32 s78, s78, s32
	s_add_u32 s74, s18, s78
	s_addc_u32 s75, s19, 0
	global_load_dwordx4 v[40:43], v36, s[74:75]
	global_load_dwordx4 v[44:47], v37, s[74:75]
	global_load_dwordx4 v[48:51], v72, s[74:75]
	global_load_dwordx4 v[52:55], v73, s[74:75]
	global_load_dwordx4 v[56:59], v74, s[74:75]
	global_load_dwordx4 v[60:63], v75, s[74:75]
	global_load_dwordx4 v[64:67], v76, s[74:75]
	global_load_dwordx4 v[68:71], v182, s[74:75]

; #define LAS __attribute__((address_space(3)))
; template <int MODE>
; __device__ __forceinline__ void transpose_item(const float* W, int N, bf16_t* WT, int ldt, int coff, LAS float* scr, int item, int lane, const float* g) {
;     const int nblk = N / 32, kb = item / nblk, nb = item % nblk, k0 = 64 * kb, n0 = 32 * nb;
; #pragma unroll 8
;     for (int i = 0; i < 32; ++i) { const int kk = 2 * i + (lane >> 5); float v = W[(size_t)(k0 + kk) * N + n0 + (lane & 31)]; if (MODE >= 1) v *= g[k0 + kk]; scr[kk * 33 + (lane & 31)] = v; }
; __global__ void __launch_bounds__(512, 2) mk_fwd(Args a) {
;     ...
;             if (r < I_O) { transpose_item<0>(a.in[I_WO], DM, WO, DM, 0, scr, r, lane, nullptr); continue; } r -= I_O;
.Ltr_st0_p0wo:
	s_cmp_lt_u32 s7, 0x800
	s_cbranch_scc0 .Ltr_nl0_p0wo
	s_lshr_b32 s15, s7, 6
	s_and_b32 s32, s7, 0x3f
	s_mul_i32 s78, s15, 0x80000
	s_lshl_b32 s32, s32, 7
	s_add_u32 s78, s78, s32
	s_add_u32 s74, s18, s78
	s_addc_u32 s75, s19, 0
	global_load_dwordx4 v[96:99], v36, s[74:75]
	global_load_dwordx4 v[100:103], v37, s[74:75]
	global_load_dwordx4 v[104:107], v72, s[74:75]
	global_load_dwordx4 v[108:111], v73, s[74:75]
	global_load_dwordx4 v[112:115], v74, s[74:75]
	global_load_dwordx4 v[116:119], v75, s[74:75]
	global_load_dwordx4 v[120:123], v76, s[74:75]
	global_load_dwordx4 v[124:127], v182, s[74:75]
	s_waitcnt vmcnt(16)
	s_branch .Ltr_pr0_p0wo
.Ltr_nl0_p0wo:
	s_sub_u32 s15, s7, 0x800
	s_cmp_lt_u32 s15, 0x800
	s_cbranch_scc0 .Ltr_w00_p0wo
	s_waitcnt vmcnt(8)
	s_branch .Ltr_pr0_p0wo

; #define LAS __attribute__((address_space(3)))
; __device__ __forceinline__ unsigned cvtpk(float lo, float hi) { f32x2_t v = {lo, hi}; bf16x2_t b = __builtin_convertvector(v, bf16x2_t); return __builtin_bit_cast(unsigned, b); }
; template <int MODE>
; __device__ __forceinline__ void transpose_item(const float* W, int N, bf16_t* WT, int ldt, int coff, LAS float* scr, int item, int lane, const float* g) {
;     ...
;     for (int i = 0; i < 32; ++i) { const int kk = 2 * i + (lane >> 5); float v = W[(size_t)(k0 + kk) * N + n0 + (lane & 31)]; if (MODE >= 1) v *= g[k0 + kk]; scr[kk * 33 + (lane & 31)] = v; }
;     asm volatile("s_waitcnt lgkmcnt(0)" ::: "memory");
;     const int c = lane & 7;
; #pragma unroll
;     for (int j = 0; j < 4; ++j) {
;         const int n = (lane >> 3) + 8 * j; const LAS float* s = scr + (8 * c) * 33 + n;
;         u32x4 o; o.x = cvtpk(s[0 * 33], s[1 * 33]); o.y = cvtpk(s[2 * 33], s[3 * 33]); o.z = cvtpk(s[4 * 33], s[5 * 33]); o.w = cvtpk(s[6 * 33], s[7 * 33]);
;         int dr = n0 + n;
;         if (MODE == 1) { dr = (dr < DFF) ? 256 * (dr >> 7) + (dr & 127) : 256 * ((dr - DFF) >> 7) + 128 + ((dr - DFF) & 127); }
;         if (MODE == 2) {
;             if (dr >= 6144) { const int t = dr - 6144, ch = t & 2047; dr = 6144 + 256 * (ch >> 7) + ((t >> 11) << 7) + (ch & 127); }
;             else if (dr >= 4096) { const int t = dr - 4096, ch = t & 1023; dr = 4096 + 256 * (ch >> 7) + ((t >> 10) << 7) + (ch & 127); }
;         }
;         *(u32x4*)(WT + (size_t)dr * ldt + coff + k0 + 8 * c) = o;
; __global__ void __launch_bounds__(512, 2) mk_fwd(Args a) {
;     ...
;             if (r < I_O) { transpose_item<0>(a.in[I_WO], DM, WO, DM, 0, scr, r, lane, nullptr); continue; } r -= I_O;
.Ltr_pr0_p0wo:
	s_add_u32 s7, s7, 0x800
	s_lshr_b32 s15, s9, 6
	s_and_b32 s32, s9, 0x3f
	s_mul_i32 s78, s32, 0x20000
	s_lshl_b32 s15, s15, 7
	s_add_u32 s78, s78, s15
	s_add_u32 s76, s94, s78
	s_addc_u32 s77, s95, 0
	ds_write_b32 v188, v4 offset:0
	ds_write_b32 v188, v5 offset:4
	ds_write_b32 v188, v6 offset:8
	ds_write_b32 v188, v7 offset:12
	ds_write_b32 v188, v8 offset:1056
	ds_write_b32 v188, v9 offset:1060
	ds_write_b32 v188, v10 offset:1064
	ds_write_b32 v188, v11 offset:1068
	ds_write_b32 v188, v12 offset:2112
	ds_write_b32 v188, v13 offset:2116
	ds_write_b32 v188, v14 offset:2120
	ds_write_b32 v188, v15 offset:2124
	ds_write_b32 v188, v16 offset:3168
	ds_write_b32 v188, v17 offset:3172
	ds_write_b32 v188, v18 offset:3176
	ds_write_b32 v188, v19 offset:3180
	ds_write_b32 v188, v20 offset:4224
	ds_write_b32 v188, v21 offset:4228
	ds_write_b32 v188, v22 offset:4232
	ds_write_b32 v188, v23 offset:4236
	ds_write_b32 v188, v24 offset:5280
	ds_write_b32 v188, v25 offset:5284
	ds_write_b32 v188, v26 offset:5288
	ds_write_b32 v188, v27 offset:5292
	ds_write_b32 v188, v28 offset:6336
	ds_write_b32 v188, v29 offset:6340
	ds_write_b32 v188, v30 offset:6344
	ds_write_b32 v188, v31 offset:6348
	ds_write_b32 v188, v32 offset:7392
	ds_write_b32 v188, v33 offset:7396
	ds_write_b32 v188, v34 offset:7400
	ds_write_b32 v188, v35 offset:7404
	s_waitcnt lgkmcnt(0)
	ds_read2_b32 v[128:129], v189 offset0:0 offset1:8
	ds_read2_b32 v[132:133], v189 offset0:33 offset1:41
	ds_read2_b32 v[136:137], v189 offset0:66 offset1:74
	ds_read2_b32 v[140:141], v189 offset0:99 offset1:107
	ds_read2_b32 v[144:145], v189 offset0:132 offset1:140
	ds_read2_b32 v[148:149], v189 offset0:165 offset1:173
	ds_read2_b32 v[152:153], v189 offset0:198 offset1:206
	ds_read2_b32 v[156:157], v189 offset0:231 offset1:239
	ds_read2_b32 v[130:131], v189 offset0:16 offset1:24
	ds_read2_b32 v[134:135], v189 offset0:49 offset1:57
	ds_read2_b32 v[138:139], v189 offset0:82 offset1:90
	ds_read2_b32 v[142:143], v189 offset0:115 offset1:123
	ds_read2_b32 v[146:147], v189 offset0:148 offset1:156
	ds_read2_b32 v[150:151], v189 offset0:181 offset1:189
	ds_read2_b32 v[154:155], v189 offset0:214 offset1:222
	ds_read2_b32 v[158:159], v189 offset0:247 offset1:255
	s_waitcnt lgkmcnt(0)
	v_cvt_pk_bf16_f32 v204, v128, v132
	v_cvt_pk_bf16_f32 v205, v136, v140
	v_cvt_pk_bf16_f32 v206, v144, v148
	v_cvt_pk_bf16_f32 v207, v152, v156
	global_store_dwordx4 v183, v[204:207], s[76:77]
	v_cvt_pk_bf16_f32 v208, v129, v133
	v_cvt_pk_bf16_f32 v209, v137, v141
	v_cvt_pk_bf16_f32 v210, v145, v149
	v_cvt_pk_bf16_f32 v211, v153, v157
	global_store_dwordx4 v184, v[208:211], s[76:77]
	v_cvt_pk_bf16_f32 v212, v130, v134
	v_cvt_pk_bf16_f32 v213, v138, v142
	v_cvt_pk_bf16_f32 v214, v146, v150
	v_cvt_pk_bf16_f32 v215, v154, v158
	global_store_dwordx4 v185, v[212:215], s[76:77]
	v_cvt_pk_bf16_f32 v216, v131, v135
	v_cvt_pk_bf16_f32 v217, v139, v143
	v_cvt_pk_bf16_f32 v218, v147, v151
	v_cvt_pk_bf16_f32 v219, v155, v159
	global_store_dwordx4 v186, v[216:219], s[76:77]
	s_add_u32 s9, s9, 0x800
	s_cmp_lt_u32 s9, 0x800
	s_cbranch_scc0 .Ltr_done_p0wo
.Ltr_st1_p0wo:
	s_cmp_lt_u32 s7, 0x800
	s_cbranch_scc0 .Ltr_nl1_p0wo
	s_lshr_b32 s15, s7, 6
	s_and_b32 s32, s7, 0x3f
	s_mul_i32 s78, s15, 0x80000
	s_lshl_b32 s32, s32, 7
	s_add_u32 s78, s78, s32
	s_add_u32 s74, s18, s78
	s_addc_u32 s75, s19, 0
	global_load_dwordx4 v[4:7], v36, s[74:75]
	global_load_dwordx4 v[8:11], v37, s[74:75]
	global_load_dwordx4 v[12:15], v72, s[74:75]
	global_load_dwordx4 v[16:19], v73, s[74:75]
	global_load_dwordx4 v[20:23], v74, s[74:75]
	global_load_dwordx4 v[24:27], v75, s[74:75]
	global_load_dwordx4 v[28:31], v76, s[74:75]
	global_load_dwordx4 v[32:35], v182, s[74:75]
	s_waitcnt vmcnt(16)
	s_branch .Ltr_pr1_p0wo

; #define LAS __attribute__((address_space(3)))
; __device__ __forceinline__ unsigned cvtpk(float lo, float hi) { f32x2_t v = {lo, hi}; bf16x2_t b = __builtin_convertvector(v, bf16x2_t); return __builtin_bit_cast(unsigned, b); }
; template <int MODE>
; __device__ __forceinline__ void transpose_item(const float* W, int N, bf16_t* WT, int ldt, int coff, LAS float* scr, int item, int lane, const float* g) {
;     ...
;     for (int i = 0; i < 32; ++i) { const int kk = 2 * i + (lane >> 5); float v = W[(size_t)(k0 + kk) * N + n0 + (lane & 31)]; if (MODE >= 1) v *= g[k0 + kk]; scr[kk * 33 + (lane & 31)] = v; }
;     asm volatile("s_waitcnt lgkmcnt(0)" ::: "memory");
;     const int c = lane & 7;
; #pragma unroll
;     for (int j = 0; j < 4; ++j) {
;         const int n = (lane >> 3) + 8 * j; const LAS float* s = scr + (8 * c) * 33 + n;
;         u32x4 o; o.x = cvtpk(s[0 * 33], s[1 * 33]); o.y = cvtpk(s[2 * 33], s[3 * 33]); o.z = cvtpk(s[4 * 33], s[5 * 33]); o.w = cvtpk(s[6 * 33], s[7 * 33]);
;         int dr = n0 + n;
;         if (MODE == 1) { dr = (dr < DFF) ? 256 * (dr >> 7) + (dr & 127) : 256 * ((dr - DFF) >> 7) + 128 + ((dr - DFF) & 127); }
;         if (MODE == 2) {
;             if (dr >= 6144) { const int t = dr - 6144, ch = t & 2047; dr = 6144 + 256 * (ch >> 7) + ((t >> 11) << 7) + (ch & 127); }
;             else if (dr >= 4096) { const int t = dr - 4096, ch = t & 1023; dr = 4096 + 256 * (ch >> 7) + ((t >> 10) << 7) + (ch & 127); }
;         }
;         *(u32x4*)(WT + (size_t)dr * ldt + coff + k0 + 8 * c) = o;
; __global__ void __launch_bounds__(512, 2) mk_fwd(Args a) {
;     ...
;             if (r < I_O) { transpose_item<0>(a.in[I_WO], DM, WO, DM, 0, scr, r, lane, nullptr); continue; } r -= I_O;
.Ltr_pr1_p0wo:
	s_add_u32 s7, s7, 0x800
	s_lshr_b32 s15, s9, 6
	s_and_b32 s32, s9, 0x3f
	s_mul_i32 s78, s32, 0x20000
	s_lshl_b32 s15, s15, 7
	s_add_u32 s78, s78, s15
	s_add_u32 s76, s94, s78
	s_addc_u32 s77, s95, 0
	ds_write_b32 v188, v40 offset:0
	ds_write_b32 v188, v41 offset:4
	ds_write_b32 v188, v42 offset:8
	ds_write_b32 v188, v43 offset:12
	ds_write_b32 v188, v44 offset:1056
	ds_write_b32 v188, v45 offset:1060
	ds_write_b32 v188, v46 offset:1064
	ds_write_b32 v188, v47 offset:1068
	ds_write_b32 v188, v48 offset:2112
	ds_write_b32 v188, v49 offset:2116
	ds_write_b32 v188, v50 offset:2120
	ds_write_b32 v188, v51 offset:2124
	ds_write_b32 v188, v52 offset:3168
	ds_write_b32 v188, v53 offset:3172
	ds_write_b32 v188, v54 offset:3176
	ds_write_b32 v188, v55 offset:3180
	ds_write_b32 v188, v56 offset:4224
	ds_write_b32 v188, v57 offset:4228
	ds_write_b32 v188, v58 offset:4232
	ds_write_b32 v188, v59 offset:4236
	ds_write_b32 v188, v60 offset:5280
	ds_write_b32 v188, v61 offset:5284
	ds_write_b32 v188, v62 offset:5288
	ds_write_b32 v188, v63 offset:5292
	ds_write_b32 v188, v64 offset:6336
	ds_write_b32 v188, v65 offset:6340
	ds_write_b32 v188, v66 offset:6344
	ds_write_b32 v188, v67 offset:6348
	ds_write_b32 v188, v68 offset:7392
	ds_write_b32 v188, v69 offset:7396
	ds_write_b32 v188, v70 offset:7400
	ds_write_b32 v188, v71 offset:7404
	s_waitcnt lgkmcnt(0)
	ds_read2_b32 v[128:129], v189 offset0:0 offset1:8
	ds_read2_b32 v[132:133], v189 offset0:33 offset1:41
	ds_read2_b32 v[136:137], v189 offset0:66 offset1:74
	ds_read2_b32 v[140:141], v189 offset0:99 offset1:107
	ds_read2_b32 v[144:145], v189 offset0:132 offset1:140
	ds_read2_b32 v[148:149], v189 offset0:165 offset1:173
	ds_read2_b32 v[152:153], v189 offset0:198 offset1:206
	ds_read2_b32 v[156:157], v189 offset0:231 offset1:239
	ds_read2_b32 v[130:131], v189 offset0:16 offset1:24
	ds_read2_b32 v[134:135], v189 offset0:49 offset1:57
	ds_read2_b32 v[138:139], v189 offset0:82 offset1:90
	ds_read2_b32 v[142:143], v189 offset0:115 offset1:123
	ds_read2_b32 v[146:147], v189 offset0:148 offset1:156
	ds_read2_b32 v[150:151], v189 offset0:181 offset1:189
	ds_read2_b32 v[154:155], v189 offset0:214 offset1:222
	ds_read2_b32 v[158:159], v189 offset0:247 offset1:255
	s_waitcnt lgkmcnt(0)
	v_cvt_pk_bf16_f32 v204, v128, v132
	v_cvt_pk_bf16_f32 v205, v136, v140
	v_cvt_pk_bf16_f32 v206, v144, v148
	v_cvt_pk_bf16_f32 v207, v152, v156
	global_store_dwordx4 v183, v[204:207], s[76:77]
	v_cvt_pk_bf16_f32 v208, v129, v133
	v_cvt_pk_bf16_f32 v209, v137, v141
	v_cvt_pk_bf16_f32 v210, v145, v149
	v_cvt_pk_bf16_f32 v211, v153, v157
	global_store_dwordx4 v184, v[208:211], s[76:77]
	v_cvt_pk_bf16_f32 v212, v130, v134
	v_cvt_pk_bf16_f32 v213, v138, v142
	v_cvt_pk_bf16_f32 v214, v146, v150
	v_cvt_pk_bf16_f32 v215, v154, v158
	global_store_dwordx4 v185, v[212:215], s[76:77]
	v_cvt_pk_bf16_f32 v216, v131, v135
	v_cvt_pk_bf16_f32 v217, v139, v143
	v_cvt_pk_bf16_f32 v218, v147, v151
	v_cvt_pk_bf16_f32 v219, v155, v159
	global_store_dwordx4 v186, v[216:219], s[76:77]
	s_add_u32 s9, s9, 0x800
	s_cmp_lt_u32 s9, 0x800
	s_cbranch_scc0 .Ltr_done_p0wo
.Ltr_st2_p0wo:
	s_cmp_lt_u32 s7, 0x800
	s_cbranch_scc0 .Ltr_nl2_p0wo
	s_lshr_b32 s15, s7, 6
	s_and_b32 s32, s7, 0x3f
	s_mul_i32 s78, s15, 0x80000
	s_lshl_b32 s32, s32, 7
	s_add_u32 s78, s78, s32
	s_add_u32 s74, s18, s78
	s_addc_u32 s75, s19, 0
	global_load_dwordx4 v[40:43], v36, s[74:75]
	global_load_dwordx4 v[44:47], v37, s[74:75]
	global_load_dwordx4 v[48:51], v72, s[74:75]
	global_load_dwordx4 v[52:55], v73, s[74:75]
	global_load_dwordx4 v[56:59], v74, s[74:75]
	global_load_dwordx4 v[60:63], v75, s[74:75]
	global_load_dwordx4 v[64:67], v76, s[74:75]
	global_load_dwordx4 v[68:71], v182, s[74:75]
	s_waitcnt vmcnt(16)
	s_branch .Ltr_pr2_p0wo

; #define LAS __attribute__((address_space(3)))
; __device__ __forceinline__ unsigned cvtpk(float lo, float hi) { f32x2_t v = {lo, hi}; bf16x2_t b = __builtin_convertvector(v, bf16x2_t); return __builtin_bit_cast(unsigned, b); }
; template <int MODE>
; __device__ __forceinline__ void transpose_item(const float* W, int N, bf16_t* WT, int ldt, int coff, LAS float* scr, int item, int lane, const float* g) {
;     ...
;     for (int i = 0; i < 32; ++i) { const int kk = 2 * i + (lane >> 5); float v = W[(size_t)(k0 + kk) * N + n0 + (lane & 31)]; if (MODE >= 1) v *= g[k0 + kk]; scr[kk * 33 + (lane & 31)] = v; }
;     asm volatile("s_waitcnt lgkmcnt(0)" ::: "memory");
;     const int c = lane & 7;
; #pragma unroll
;     for (int j = 0; j < 4; ++j) {
;         const int n = (lane >> 3) + 8 * j; const LAS float* s = scr + (8 * c) * 33 + n;
;         u32x4 o; o.x = cvtpk(s[0 * 33], s[1 * 33]); o.y = cvtpk(s[2 * 33], s[3 * 33]); o.z = cvtpk(s[4 * 33], s[5 * 33]); o.w = cvtpk(s[6 * 33], s[7 * 33]);
;         int dr = n0 + n;
;         if (MODE == 1) { dr = (dr < DFF) ? 256 * (dr >> 7) + (dr & 127) : 256 * ((dr - DFF) >> 7) + 128 + ((dr - DFF) & 127); }
;         if (MODE == 2) {
;             if (dr >= 6144) { const int t = dr - 6144, ch = t & 2047; dr = 6144 + 256 * (ch >> 7) + ((t >> 11) << 7) + (ch & 127); }
;             else if (dr >= 4096) { const int t = dr - 4096, ch = t & 1023; dr = 4096 + 256 * (ch >> 7) + ((t >> 10) << 7) + (ch & 127); }
;         }
;         *(u32x4*)(WT + (size_t)dr * ldt + coff + k0 + 8 * c) = o;
; __global__ void __launch_bounds__(512, 2) mk_fwd(Args a) {
;     ...
;             { const int bb = r / I_V; transpose_item<0>(a.in[I_CV] + (size_t)bb * PAST * 1024, 1024, VTC + (size_t)bb * 1024 * PAST, PAST, 0, scr, r % I_V, lane, nullptr); }
.Ltr_pr2_p0wo:
	s_add_u32 s7, s7, 0x800
	s_lshr_b32 s15, s9, 6
	s_and_b32 s32, s9, 0x3f
	s_mul_i32 s78, s32, 0x20000
	s_lshl_b32 s15, s15, 7
	s_add_u32 s78, s78, s15
	s_add_u32 s76, s94, s78
	s_addc_u32 s77, s95, 0
	ds_write_b32 v188, v96 offset:0
	ds_write_b32 v188, v97 offset:4
	ds_write_b32 v188, v98 offset:8
	ds_write_b32 v188, v99 offset:12
	ds_write_b32 v188, v100 offset:1056
	ds_write_b32 v188, v101 offset:1060
	ds_write_b32 v188, v102 offset:1064
	ds_write_b32 v188, v103 offset:1068
	ds_write_b32 v188, v104 offset:2112
	ds_write_b32 v188, v105 offset:2116
	ds_write_b32 v188, v106 offset:2120
	ds_write_b32 v188, v107 offset:2124
	ds_write_b32 v188, v108 offset:3168
	ds_write_b32 v188, v109 offset:3172
	ds_write_b32 v188, v110 offset:3176
	ds_write_b32 v188, v111 offset:3180
	ds_write_b32 v188, v112 offset:4224
	ds_write_b32 v188, v113 offset:4228
	ds_write_b32 v188, v114 offset:4232
	ds_write_b32 v188, v115 offset:4236
	ds_write_b32 v188, v116 offset:5280
	ds_write_b32 v188, v117 offset:5284
	ds_write_b32 v188, v118 offset:5288
	ds_write_b32 v188, v119 offset:5292
	ds_write_b32 v188, v120 offset:6336
	ds_write_b32 v188, v121 offset:6340
	ds_write_b32 v188, v122 offset:6344
	ds_write_b32 v188, v123 offset:6348
	ds_write_b32 v188, v124 offset:7392
	ds_write_b32 v188, v125 offset:7396
	ds_write_b32 v188, v126 offset:7400
	ds_write_b32 v188, v127 offset:7404
	s_waitcnt lgkmcnt(0)
	ds_read2_b32 v[128:129], v189 offset0:0 offset1:8
	ds_read2_b32 v[132:133], v189 offset0:33 offset1:41
	ds_read2_b32 v[136:137], v189 offset0:66 offset1:74
	ds_read2_b32 v[140:141], v189 offset0:99 offset1:107
	ds_read2_b32 v[144:145], v189 offset0:132 offset1:140
	ds_read2_b32 v[148:149], v189 offset0:165 offset1:173
	ds_read2_b32 v[152:153], v189 offset0:198 offset1:206
	ds_read2_b32 v[156:157], v189 offset0:231 offset1:239
	ds_read2_b32 v[130:131], v189 offset0:16 offset1:24
	ds_read2_b32 v[134:135], v189 offset0:49 offset1:57
	ds_read2_b32 v[138:139], v189 offset0:82 offset1:90
	ds_read2_b32 v[142:143], v189 offset0:115 offset1:123
	ds_read2_b32 v[146:147], v189 offset0:148 offset1:156
	ds_read2_b32 v[150:151], v189 offset0:181 offset1:189
	ds_read2_b32 v[154:155], v189 offset0:214 offset1:222
	ds_read2_b32 v[158:159], v189 offset0:247 offset1:255
	s_waitcnt lgkmcnt(0)
	v_cvt_pk_bf16_f32 v204, v128, v132
	v_cvt_pk_bf16_f32 v205, v136, v140
	v_cvt_pk_bf16_f32 v206, v144, v148
	v_cvt_pk_bf16_f32 v207, v152, v156
	global_store_dwordx4 v183, v[204:207], s[76:77]
	v_cvt_pk_bf16_f32 v208, v129, v133
	v_cvt_pk_bf16_f32 v209, v137, v141
	v_cvt_pk_bf16_f32 v210, v145, v149
	v_cvt_pk_bf16_f32 v211, v153, v157
	global_store_dwordx4 v184, v[208:211], s[76:77]
	v_cvt_pk_bf16_f32 v212, v130, v134
	v_cvt_pk_bf16_f32 v213, v138, v142
	v_cvt_pk_bf16_f32 v214, v146, v150
	v_cvt_pk_bf16_f32 v215, v154, v158
	global_store_dwordx4 v185, v[212:215], s[76:77]
	v_cvt_pk_bf16_f32 v216, v131, v135
	v_cvt_pk_bf16_f32 v217, v139, v143
	v_cvt_pk_bf16_f32 v218, v147, v151
	v_cvt_pk_bf16_f32 v219, v155, v159
	global_store_dwordx4 v186, v[216:219], s[76:77]
	s_add_u32 s9, s9, 0x800
	s_cmp_lt_u32 s9, 0x800
	s_cbranch_scc0 .Ltr_done_p0wo
	s_branch .Ltr_st0_p0wo
.Ltr_done_p0wo:
	s_cmp_lt_u32 s96, 0x2000
	s_cbranch_scc0 .Ltr_done_p0vt
	v_lshrrev_b32_e32 v0, 3, v220
	v_and_b32_e32 v1, 7, v220
	v_mul_u32_u24_e32 v2, 0x1000, v0
	v_lshl_add_u32 v36, v1, 4, v2
	v_add_u32_e32 v37, 0x8000, v36
	v_add_u32_e32 v72, 0x10000, v36
	v_add_u32_e32 v73, 0x18000, v36
	v_add_u32_e32 v74, 0x20000, v36
	v_add_u32_e32 v75, 0x28000, v36
	v_add_u32_e32 v76, 0x30000, v36
	v_add_u32_e32 v182, 0x38000, v36
	v_mul_u32_u24_e32 v2, 0x84, v0
	v_lshl_add_u32 v2, v1, 4, v2
	v_add_u32_e32 v188, s0, v2
	v_mul_u32_u24_e32 v2, 0x420, v1
	v_lshl_add_u32 v2, v0, 2, v2
	v_add_u32_e32 v189, s0, v2
	v_mul_u32_u24_e32 v2, 0x800, v0
	v_lshl_add_u32 v183, v1, 4, v2
	v_add_u32_e32 v184, 0x4000, v183
	v_add_u32_e32 v185, 0x8000, v183
	v_add_u32_e32 v186, 0xc000, v183
	s_mov_b32 s9, s96
	s_mov_b32 s7, s96
	s_lshr_b32 s79, s7, 9
	s_and_b32 s78, s7, 0x1ff
	s_lshr_b32 s15, s78, 5
	s_and_b32 s32, s78, 0x1f
	s_mul_i32 s78, s15, 0x40000
	s_lshl_b32 s32, s32, 7
	s_add_u32 s78, s78, s32
	s_mul_i32 s32, s79, 0x400000
	s_add_u32 s78, s78, s32
	s_add_u32 s74, s42, s78
	s_addc_u32 s75, s43, 0
	global_load_dwordx4 v[4:7], v36, s[74:75]
	global_load_dwordx4 v[8:11], v37, s[74:75]
	global_load_dwordx4 v[12:15], v72, s[74:75]
	global_load_dwordx4 v[16:19], v73, s[74:75]
	global_load_dwordx4 v[20:23], v74, s[74:75]
	global_load_dwordx4 v[24:27], v75, s[74:75]
	global_load_dwordx4 v[28:31], v76, s[74:75]
	global_load_dwordx4 v[32:35], v182, s[74:75]
	s_add_u32 s7, s7, 0x800
	s_cmp_lt_u32 s7, 0x2000
	s_cbranch_scc0 .Ltr_p1_p0vt
	s_lshr_b32 s79, s7, 9
	s_and_b32 s78, s7, 0x1ff
	s_lshr_b32 s15, s78, 5
	s_and_b32 s32, s78, 0x1f
	s_mul_i32 s78, s15, 0x40000
	s_lshl_b32 s32, s32, 7
	s_add_u32 s78, s78, s32
	s_mul_i32 s32, s79, 0x400000
	s_add_u32 s78, s78, s32
	s_add_u32 s74, s42, s78
	s_addc_u32 s75, s43, 0
	global_load_dwordx4 v[40:43], v36, s[74:75]
	global_load_dwordx4 v[44:47], v37, s[74:75]
	global_load_dwordx4 v[48:51], v72, s[74:75]
	global_load_dwordx4 v[52:55], v73, s[74:75]
	global_load_dwordx4 v[56:59], v74, s[74:75]
	global_load_dwordx4 v[60:63], v75, s[74:75]
	global_load_dwordx4 v[64:67], v76, s[74:75]
	global_load_dwordx4 v[68:71], v182, s[74:75]

; #define LAS __attribute__((address_space(3)))
; template <int MODE>
; __device__ __forceinline__ void transpose_item(const float* W, int N, bf16_t* WT, int ldt, int coff, LAS float* scr, int item, int lane, const float* g) {
;     const int nblk = N / 32, kb = item / nblk, nb = item % nblk, k0 = 64 * kb, n0 = 32 * nb;
; #pragma unroll 8
;     for (int i = 0; i < 32; ++i) { const int kk = 2 * i + (lane >> 5); float v = W[(size_t)(k0 + kk) * N + n0 + (lane & 31)]; if (MODE >= 1) v *= g[k0 + kk]; scr[kk * 33 + (lane & 31)] = v; }
; __global__ void __launch_bounds__(512, 2) mk_fwd(Args a) {
;     ...
;             { const int bb = r / I_V; transpose_item<0>(a.in[I_CV] + (size_t)bb * PAST * 1024, 1024, VTC + (size_t)bb * 1024 * PAST, PAST, 0, scr, r % I_V, lane, nullptr); }
.Ltr_st0_p0vt:
	s_cmp_lt_u32 s7, 0x2000
	s_cbranch_scc0 .Ltr_nl0_p0vt
	s_lshr_b32 s79, s7, 9
	s_and_b32 s78, s7, 0x1ff
	s_lshr_b32 s15, s78, 5
	s_and_b32 s32, s78, 0x1f
	s_mul_i32 s78, s15, 0x40000
	s_lshl_b32 s32, s32, 7
	s_add_u32 s78, s78, s32
	s_mul_i32 s32, s79, 0x400000
	s_add_u32 s78, s78, s32
	s_add_u32 s74, s42, s78
	s_addc_u32 s75, s43, 0
	global_load_dwordx4 v[96:99], v36, s[74:75]
	global_load_dwordx4 v[100:103], v37, s[74:75]
	global_load_dwordx4 v[104:107], v72, s[74:75]
	global_load_dwordx4 v[108:111], v73, s[74:75]
	global_load_dwordx4 v[112:115], v74, s[74:75]
	global_load_dwordx4 v[116:119], v75, s[74:75]
	global_load_dwordx4 v[120:123], v76, s[74:75]
	global_load_dwordx4 v[124:127], v182, s[74:75]
	s_waitcnt vmcnt(16)
	s_branch .Ltr_pr0_p0vt
.Ltr_nl0_p0vt:
	s_sub_u32 s15, s7, 0x800
	s_cmp_lt_u32 s15, 0x2000
	s_cbranch_scc0 .Ltr_w00_p0vt
	s_waitcnt vmcnt(8)
	s_branch .Ltr_pr0_p0vt

; #define LAS __attribute__((address_space(3)))
; __device__ __forceinline__ unsigned cvtpk(float lo, float hi) { f32x2_t v = {lo, hi}; bf16x2_t b = __builtin_convertvector(v, bf16x2_t); return __builtin_bit_cast(unsigned, b); }
; template <int MODE>
; __device__ __forceinline__ void transpose_item(const float* W, int N, bf16_t* WT, int ldt, int coff, LAS float* scr, int item, int lane, const float* g) {
;     ...
;     for (int i = 0; i < 32; ++i) { const int kk = 2 * i + (lane >> 5); float v = W[(size_t)(k0 + kk) * N + n0 + (lane & 31)]; if (MODE >= 1) v *= g[k0 + kk]; scr[kk * 33 + (lane & 31)] = v; }
;     asm volatile("s_waitcnt lgkmcnt(0)" ::: "memory");
;     const int c = lane & 7;
; #pragma unroll
;     for (int j = 0; j < 4; ++j) {
;         const int n = (lane >> 3) + 8 * j; const LAS float* s = scr + (8 * c) * 33 + n;
;         u32x4 o; o.x = cvtpk(s[0 * 33], s[1 * 33]); o.y = cvtpk(s[2 * 33], s[3 * 33]); o.z = cvtpk(s[4 * 33], s[5 * 33]); o.w = cvtpk(s[6 * 33], s[7 * 33]);
;         int dr = n0 + n;
;         if (MODE == 1) { dr = (dr < DFF) ? 256 * (dr >> 7) + (dr & 127) : 256 * ((dr - DFF) >> 7) + 128 + ((dr - DFF) & 127); }
;         if (MODE == 2) {
;             if (dr >= 6144) { const int t = dr - 6144, ch = t & 2047; dr = 6144 + 256 * (ch >> 7) + ((t >> 11) << 7) + (ch & 127); }
;             else if (dr >= 4096) { const int t = dr - 4096, ch = t & 1023; dr = 4096 + 256 * (ch >> 7) + ((t >> 10) << 7) + (ch & 127); }
;         }
;         *(u32x4*)(WT + (size_t)dr * ldt + coff + k0 + 8 * c) = o;
; __global__ void __launch_bounds__(512, 2) mk_fwd(Args a) {
;     ...
;             { const int bb = r / I_V; transpose_item<0>(a.in[I_CV] + (size_t)bb * PAST * 1024, 1024, VTC + (size_t)bb * 1024 * PAST, PAST, 0, scr, r % I_V, lane, nullptr); }
.Ltr_pr0_p0vt:
	s_add_u32 s7, s7, 0x800
	s_lshr_b32 s79, s9, 9
	s_and_b32 s78, s9, 0x1ff
	s_lshr_b32 s15, s78, 5
	s_and_b32 s32, s78, 0x1f
	s_mul_i32 s78, s32, 0x10000
	s_lshl_b32 s15, s15, 7
	s_add_u32 s78, s78, s15
	s_mul_i32 s32, s79, 0x200000
	s_add_u32 s78, s78, s32
	s_add_u32 s76, s72, s78
	s_addc_u32 s77, s73, 0
	ds_write_b32 v188, v4 offset:0
	ds_write_b32 v188, v5 offset:4
	ds_write_b32 v188, v6 offset:8
	ds_write_b32 v188, v7 offset:12
	ds_write_b32 v188, v8 offset:1056
	ds_write_b32 v188, v9 offset:1060
	ds_write_b32 v188, v10 offset:1064
	ds_write_b32 v188, v11 offset:1068
	ds_write_b32 v188, v12 offset:2112
	ds_write_b32 v188, v13 offset:2116
	ds_write_b32 v188, v14 offset:2120
	ds_write_b32 v188, v15 offset:2124
	ds_write_b32 v188, v16 offset:3168
	ds_write_b32 v188, v17 offset:3172
	ds_write_b32 v188, v18 offset:3176
	ds_write_b32 v188, v19 offset:3180
	ds_write_b32 v188, v20 offset:4224
	ds_write_b32 v188, v21 offset:4228
	ds_write_b32 v188, v22 offset:4232
	ds_write_b32 v188, v23 offset:4236
	ds_write_b32 v188, v24 offset:5280
	ds_write_b32 v188, v25 offset:5284
	ds_write_b32 v188, v26 offset:5288
	ds_write_b32 v188, v27 offset:5292
	ds_write_b32 v188, v28 offset:6336
	ds_write_b32 v188, v29 offset:6340
	ds_write_b32 v188, v30 offset:6344
	ds_write_b32 v188, v31 offset:6348
	ds_write_b32 v188, v32 offset:7392
	ds_write_b32 v188, v33 offset:7396
	ds_write_b32 v188, v34 offset:7400
	ds_write_b32 v188, v35 offset:7404
	s_waitcnt lgkmcnt(0)
	ds_read2_b32 v[128:129], v189 offset0:0 offset1:8
	ds_read2_b32 v[132:133], v189 offset0:33 offset1:41
	ds_read2_b32 v[136:137], v189 offset0:66 offset1:74
	ds_read2_b32 v[140:141], v189 offset0:99 offset1:107
	ds_read2_b32 v[144:145], v189 offset0:132 offset1:140
	ds_read2_b32 v[148:149], v189 offset0:165 offset1:173
	ds_read2_b32 v[152:153], v189 offset0:198 offset1:206
	ds_read2_b32 v[156:157], v189 offset0:231 offset1:239
	ds_read2_b32 v[130:131], v189 offset0:16 offset1:24
	ds_read2_b32 v[134:135], v189 offset0:49 offset1:57
	ds_read2_b32 v[138:139], v189 offset0:82 offset1:90
	ds_read2_b32 v[142:143], v189 offset0:115 offset1:123
	ds_read2_b32 v[146:147], v189 offset0:148 offset1:156
	ds_read2_b32 v[150:151], v189 offset0:181 offset1:189
	ds_read2_b32 v[154:155], v189 offset0:214 offset1:222
	ds_read2_b32 v[158:159], v189 offset0:247 offset1:255
	s_waitcnt lgkmcnt(0)
	v_cvt_pk_bf16_f32 v204, v128, v132
	v_cvt_pk_bf16_f32 v205, v136, v140
	v_cvt_pk_bf16_f32 v206, v144, v148
	v_cvt_pk_bf16_f32 v207, v152, v156
	global_store_dwordx4 v183, v[204:207], s[76:77]
	v_cvt_pk_bf16_f32 v208, v129, v133
	v_cvt_pk_bf16_f32 v209, v137, v141
	v_cvt_pk_bf16_f32 v210, v145, v149
	v_cvt_pk_bf16_f32 v211, v153, v157
	global_store_dwordx4 v184, v[208:211], s[76:77]
	v_cvt_pk_bf16_f32 v212, v130, v134
	v_cvt_pk_bf16_f32 v213, v138, v142
	v_cvt_pk_bf16_f32 v214, v146, v150
	v_cvt_pk_bf16_f32 v215, v154, v158
	global_store_dwordx4 v185, v[212:215], s[76:77]
	v_cvt_pk_bf16_f32 v216, v131, v135
	v_cvt_pk_bf16_f32 v217, v139, v143
	v_cvt_pk_bf16_f32 v218, v147, v151
	v_cvt_pk_bf16_f32 v219, v155, v159
	global_store_dwordx4 v186, v[216:219], s[76:77]
	s_add_u32 s9, s9, 0x800
	s_cmp_lt_u32 s9, 0x2000
	s_cbranch_scc0 .Ltr_done_p0vt
.Ltr_st1_p0vt:
	s_cmp_lt_u32 s7, 0x2000
	s_cbranch_scc0 .Ltr_nl1_p0vt
	s_lshr_b32 s79, s7, 9
	s_and_b32 s78, s7, 0x1ff
	s_lshr_b32 s15, s78, 5
	s_and_b32 s32, s78, 0x1f
	s_mul_i32 s78, s15, 0x40000
	s_lshl_b32 s32, s32, 7
	s_add_u32 s78, s78, s32
	s_mul_i32 s32, s79, 0x400000
	s_add_u32 s78, s78, s32
	s_add_u32 s74, s42, s78
	s_addc_u32 s75, s43, 0
	global_load_dwordx4 v[4:7], v36, s[74:75]
	global_load_dwordx4 v[8:11], v37, s[74:75]
	global_load_dwordx4 v[12:15], v72, s[74:75]
	global_load_dwordx4 v[16:19], v73, s[74:75]
	global_load_dwordx4 v[20:23], v74, s[74:75]
	global_load_dwordx4 v[24:27], v75, s[74:75]
	global_load_dwordx4 v[28:31], v76, s[74:75]
	global_load_dwordx4 v[32:35], v182, s[74:75]
	s_waitcnt vmcnt(16)
	s_branch .Ltr_pr1_p0vt

; #define LAS __attribute__((address_space(3)))
; __device__ __forceinline__ unsigned cvtpk(float lo, float hi) { f32x2_t v = {lo, hi}; bf16x2_t b = __builtin_convertvector(v, bf16x2_t); return __builtin_bit_cast(unsigned, b); }
; template <int MODE>
; __device__ __forceinline__ void transpose_item(const float* W, int N, bf16_t* WT, int ldt, int coff, LAS float* scr, int item, int lane, const float* g) {
;     ...
;     for (int i = 0; i < 32; ++i) { const int kk = 2 * i + (lane >> 5); float v = W[(size_t)(k0 + kk) * N + n0 + (lane & 31)]; if (MODE >= 1) v *= g[k0 + kk]; scr[kk * 33 + (lane & 31)] = v; }
;     asm volatile("s_waitcnt lgkmcnt(0)" ::: "memory");
;     const int c = lane & 7;
; #pragma unroll
;     for (int j = 0; j < 4; ++j) {
;         const int n = (lane >> 3) + 8 * j; const LAS float* s = scr + (8 * c) * 33 + n;
;         u32x4 o; o.x = cvtpk(s[0 * 33], s[1 * 33]); o.y = cvtpk(s[2 * 33], s[3 * 33]); o.z = cvtpk(s[4 * 33], s[5 * 33]); o.w = cvtpk(s[6 * 33], s[7 * 33]);
;         int dr = n0 + n;
;         if (MODE == 1) { dr = (dr < DFF) ? 256 * (dr >> 7) + (dr & 127) : 256 * ((dr - DFF) >> 7) + 128 + ((dr - DFF) & 127); }
;         if (MODE == 2) {
;             if (dr >= 6144) { const int t = dr - 6144, ch = t & 2047; dr = 6144 + 256 * (ch >> 7) + ((t >> 11) << 7) + (ch & 127); }
;             else if (dr >= 4096) { const int t = dr - 4096, ch = t & 1023; dr = 4096 + 256 * (ch >> 7) + ((t >> 10) << 7) + (ch & 127); }
;         }
;         *(u32x4*)(WT + (size_t)dr * ldt + coff + k0 + 8 * c) = o;
; __global__ void __launch_bounds__(512, 2) mk_fwd(Args a) {
;     ...
;             { const int bb = r / I_V; transpose_item<0>(a.in[I_CV] + (size_t)bb * PAST * 1024, 1024, VTC + (size_t)bb * 1024 * PAST, PAST, 0, scr, r % I_V, lane, nullptr); }
.Ltr_pr1_p0vt:
	s_add_u32 s7, s7, 0x800
	s_lshr_b32 s79, s9, 9
	s_and_b32 s78, s9, 0x1ff
	s_lshr_b32 s15, s78, 5
	s_and_b32 s32, s78, 0x1f
	s_mul_i32 s78, s32, 0x10000
	s_lshl_b32 s15, s15, 7
	s_add_u32 s78, s78, s15
	s_mul_i32 s32, s79, 0x200000
	s_add_u32 s78, s78, s32
	s_add_u32 s76, s72, s78
	s_addc_u32 s77, s73, 0
	ds_write_b32 v188, v40 offset:0
	ds_write_b32 v188, v41 offset:4
	ds_write_b32 v188, v42 offset:8
	ds_write_b32 v188, v43 offset:12
	ds_write_b32 v188, v44 offset:1056
	ds_write_b32 v188, v45 offset:1060
	ds_write_b32 v188, v46 offset:1064
	ds_write_b32 v188, v47 offset:1068
	ds_write_b32 v188, v48 offset:2112
	ds_write_b32 v188, v49 offset:2116
	ds_write_b32 v188, v50 offset:2120
	ds_write_b32 v188, v51 offset:2124
	ds_write_b32 v188, v52 offset:3168
	ds_write_b32 v188, v53 offset:3172
	ds_write_b32 v188, v54 offset:3176
	ds_write_b32 v188, v55 offset:3180
	ds_write_b32 v188, v56 offset:4224
	ds_write_b32 v188, v57 offset:4228
	ds_write_b32 v188, v58 offset:4232
	ds_write_b32 v188, v59 offset:4236
	ds_write_b32 v188, v60 offset:5280
	ds_write_b32 v188, v61 offset:5284
	ds_write_b32 v188, v62 offset:5288
	ds_write_b32 v188, v63 offset:5292
	ds_write_b32 v188, v64 offset:6336
	ds_write_b32 v188, v65 offset:6340
	ds_write_b32 v188, v66 offset:6344
	ds_write_b32 v188, v67 offset:6348
	ds_write_b32 v188, v68 offset:7392
	ds_write_b32 v188, v69 offset:7396
	ds_write_b32 v188, v70 offset:7400
	ds_write_b32 v188, v71 offset:7404
	s_waitcnt lgkmcnt(0)
	ds_read2_b32 v[128:129], v189 offset0:0 offset1:8
	ds_read2_b32 v[132:133], v189 offset0:33 offset1:41
	ds_read2_b32 v[136:137], v189 offset0:66 offset1:74
	ds_read2_b32 v[140:141], v189 offset0:99 offset1:107
	ds_read2_b32 v[144:145], v189 offset0:132 offset1:140
	ds_read2_b32 v[148:149], v189 offset0:165 offset1:173
	ds_read2_b32 v[152:153], v189 offset0:198 offset1:206
	ds_read2_b32 v[156:157], v189 offset0:231 offset1:239
	ds_read2_b32 v[130:131], v189 offset0:16 offset1:24
	ds_read2_b32 v[134:135], v189 offset0:49 offset1:57
	ds_read2_b32 v[138:139], v189 offset0:82 offset1:90
	ds_read2_b32 v[142:143], v189 offset0:115 offset1:123
	ds_read2_b32 v[146:147], v189 offset0:148 offset1:156
	ds_read2_b32 v[150:151], v189 offset0:181 offset1:189
	ds_read2_b32 v[154:155], v189 offset0:214 offset1:222
	ds_read2_b32 v[158:159], v189 offset0:247 offset1:255
	s_waitcnt lgkmcnt(0)
	v_cvt_pk_bf16_f32 v204, v128, v132
	v_cvt_pk_bf16_f32 v205, v136, v140
	v_cvt_pk_bf16_f32 v206, v144, v148
	v_cvt_pk_bf16_f32 v207, v152, v156
	global_store_dwordx4 v183, v[204:207], s[76:77]
	v_cvt_pk_bf16_f32 v208, v129, v133
	v_cvt_pk_bf16_f32 v209, v137, v141
	v_cvt_pk_bf16_f32 v210, v145, v149
	v_cvt_pk_bf16_f32 v211, v153, v157
	global_store_dwordx4 v184, v[208:211], s[76:77]
	v_cvt_pk_bf16_f32 v212, v130, v134
	v_cvt_pk_bf16_f32 v213, v138, v142
	v_cvt_pk_bf16_f32 v214, v146, v150
	v_cvt_pk_bf16_f32 v215, v154, v158
	global_store_dwordx4 v185, v[212:215], s[76:77]
	v_cvt_pk_bf16_f32 v216, v131, v135
	v_cvt_pk_bf16_f32 v217, v139, v143
	v_cvt_pk_bf16_f32 v218, v147, v151
	v_cvt_pk_bf16_f32 v219, v155, v159
	global_store_dwordx4 v186, v[216:219], s[76:77]
	s_add_u32 s9, s9, 0x800
	s_cmp_lt_u32 s9, 0x2000
	s_cbranch_scc0 .Ltr_done_p0vt
.Ltr_st2_p0vt:
	s_cmp_lt_u32 s7, 0x2000
	s_cbranch_scc0 .Ltr_nl2_p0vt
	s_lshr_b32 s79, s7, 9
	s_and_b32 s78, s7, 0x1ff
	s_lshr_b32 s15, s78, 5
	s_and_b32 s32, s78, 0x1f
	s_mul_i32 s78, s15, 0x40000
	s_lshl_b32 s32, s32, 7
	s_add_u32 s78, s78, s32
	s_mul_i32 s32, s79, 0x400000
	s_add_u32 s78, s78, s32
	s_add_u32 s74, s42, s78
	s_addc_u32 s75, s43, 0
	global_load_dwordx4 v[40:43], v36, s[74:75]
	global_load_dwordx4 v[44:47], v37, s[74:75]
	global_load_dwordx4 v[48:51], v72, s[74:75]
	global_load_dwordx4 v[52:55], v73, s[74:75]
	global_load_dwordx4 v[56:59], v74, s[74:75]
	global_load_dwordx4 v[60:63], v75, s[74:75]
	global_load_dwordx4 v[64:67], v76, s[74:75]
	global_load_dwordx4 v[68:71], v182, s[74:75]
	s_waitcnt vmcnt(16)
	s_branch .Ltr_pr2_p0vt

; #define LAS __attribute__((address_space(3)))
; __device__ __forceinline__ unsigned cvtpk(float lo, float hi) { f32x2_t v = {lo, hi}; bf16x2_t b = __builtin_convertvector(v, bf16x2_t); return __builtin_bit_cast(unsigned, b); }
; template <int MODE>
; __device__ __forceinline__ void transpose_item(const float* W, int N, bf16_t* WT, int ldt, int coff, LAS float* scr, int item, int lane, const float* g) {
;     ...
;     for (int i = 0; i < 32; ++i) { const int kk = 2 * i + (lane >> 5); float v = W[(size_t)(k0 + kk) * N + n0 + (lane & 31)]; if (MODE >= 1) v *= g[k0 + kk]; scr[kk * 33 + (lane & 31)] = v; }
;     asm volatile("s_waitcnt lgkmcnt(0)" ::: "memory");
;     const int c = lane & 7;
; #pragma unroll
;     for (int j = 0; j < 4; ++j) {
;         const int n = (lane >> 3) + 8 * j; const LAS float* s = scr + (8 * c) * 33 + n;
;         u32x4 o; o.x = cvtpk(s[0 * 33], s[1 * 33]); o.y = cvtpk(s[2 * 33], s[3 * 33]); o.z = cvtpk(s[4 * 33], s[5 * 33]); o.w = cvtpk(s[6 * 33], s[7 * 33]);
;         int dr = n0 + n;
;         if (MODE == 1) { dr = (dr < DFF) ? 256 * (dr >> 7) + (dr & 127) : 256 * ((dr - DFF) >> 7) + 128 + ((dr - DFF) & 127); }
;         if (MODE == 2) {
;             if (dr >= 6144) { const int t = dr - 6144, ch = t & 2047; dr = 6144 + 256 * (ch >> 7) + ((t >> 11) << 7) + (ch & 127); }
;             else if (dr >= 4096) { const int t = dr - 4096, ch = t & 1023; dr = 4096 + 256 * (ch >> 7) + ((t >> 10) << 7) + (ch & 127); }
;         }
;         *(u32x4*)(WT + (size_t)dr * ldt + coff + k0 + 8 * c) = o;
; __global__ void __launch_bounds__(512, 2) mk_fwd(Args a) {
;     ...
;         for (int m = gw; m < MTOT; m += NGW) {
;             const float* xr = (m < MP) ? a.in[I_XP] + (size_t)m * DM : a.in[I_XS] + (size_t)(m - MP) * DM;
;             f32x4 v[8]; float s = 0.f;
; #pragma unroll
;             for (int j = 0; j < 8; ++j) { v[j] = *(const f32x4*)(xr + 4 * lane + 256 * j); s += (v[j][0] * v[j][0] + v[j][1] * v[j][1]) + (v[j][2] * v[j][2] + v[j][3] * v[j][3]); }
;             const float rstd = __builtin_amdgcn_rsqf(wave_sum(s) * (1.0f / DM) + EPS);
;             if (lane == 0) rstd1[m] = rstd;
.Ltr_pr2_p0vt:
	s_add_u32 s7, s7, 0x800
	s_lshr_b32 s79, s9, 9
	s_and_b32 s78, s9, 0x1ff
	s_lshr_b32 s15, s78, 5
	s_and_b32 s32, s78, 0x1f
	s_mul_i32 s78, s32, 0x10000
	s_lshl_b32 s15, s15, 7
	s_add_u32 s78, s78, s15
	s_mul_i32 s32, s79, 0x200000
	s_add_u32 s78, s78, s32
	s_add_u32 s76, s72, s78
	s_addc_u32 s77, s73, 0
	ds_write_b32 v188, v96 offset:0
	ds_write_b32 v188, v97 offset:4
	ds_write_b32 v188, v98 offset:8
	ds_write_b32 v188, v99 offset:12
	ds_write_b32 v188, v100 offset:1056
	ds_write_b32 v188, v101 offset:1060
	ds_write_b32 v188, v102 offset:1064
	ds_write_b32 v188, v103 offset:1068
	ds_write_b32 v188, v104 offset:2112
	ds_write_b32 v188, v105 offset:2116
	ds_write_b32 v188, v106 offset:2120
	ds_write_b32 v188, v107 offset:2124
	ds_write_b32 v188, v108 offset:3168
	ds_write_b32 v188, v109 offset:3172
	ds_write_b32 v188, v110 offset:3176
	ds_write_b32 v188, v111 offset:3180
	ds_write_b32 v188, v112 offset:4224
	ds_write_b32 v188, v113 offset:4228
	ds_write_b32 v188, v114 offset:4232
	ds_write_b32 v188, v115 offset:4236
	ds_write_b32 v188, v116 offset:5280
	ds_write_b32 v188, v117 offset:5284
	ds_write_b32 v188, v118 offset:5288
	ds_write_b32 v188, v119 offset:5292
	ds_write_b32 v188, v120 offset:6336
	ds_write_b32 v188, v121 offset:6340
	ds_write_b32 v188, v122 offset:6344
	ds_write_b32 v188, v123 offset:6348
	ds_write_b32 v188, v124 offset:7392
	ds_write_b32 v188, v125 offset:7396
	ds_write_b32 v188, v126 offset:7400
	ds_write_b32 v188, v127 offset:7404
	s_waitcnt lgkmcnt(0)
	ds_read2_b32 v[128:129], v189 offset0:0 offset1:8
	ds_read2_b32 v[132:133], v189 offset0:33 offset1:41
	ds_read2_b32 v[136:137], v189 offset0:66 offset1:74
	ds_read2_b32 v[140:141], v189 offset0:99 offset1:107
	ds_read2_b32 v[144:145], v189 offset0:132 offset1:140
	ds_read2_b32 v[148:149], v189 offset0:165 offset1:173
	ds_read2_b32 v[152:153], v189 offset0:198 offset1:206
	ds_read2_b32 v[156:157], v189 offset0:231 offset1:239
	ds_read2_b32 v[130:131], v189 offset0:16 offset1:24
	ds_read2_b32 v[134:135], v189 offset0:49 offset1:57
	ds_read2_b32 v[138:139], v189 offset0:82 offset1:90
	ds_read2_b32 v[142:143], v189 offset0:115 offset1:123
	ds_read2_b32 v[146:147], v189 offset0:148 offset1:156
	ds_read2_b32 v[150:151], v189 offset0:181 offset1:189
	ds_read2_b32 v[154:155], v189 offset0:214 offset1:222
	ds_read2_b32 v[158:159], v189 offset0:247 offset1:255
	s_waitcnt lgkmcnt(0)
	v_cvt_pk_bf16_f32 v204, v128, v132
	v_cvt_pk_bf16_f32 v205, v136, v140
	v_cvt_pk_bf16_f32 v206, v144, v148
	v_cvt_pk_bf16_f32 v207, v152, v156
	global_store_dwordx4 v183, v[204:207], s[76:77]
	v_cvt_pk_bf16_f32 v208, v129, v133
	v_cvt_pk_bf16_f32 v209, v137, v141
	v_cvt_pk_bf16_f32 v210, v145, v149
	v_cvt_pk_bf16_f32 v211, v153, v157
	global_store_dwordx4 v184, v[208:211], s[76:77]
	v_cvt_pk_bf16_f32 v212, v130, v134
	v_cvt_pk_bf16_f32 v213, v138, v142
	v_cvt_pk_bf16_f32 v214, v146, v150
	v_cvt_pk_bf16_f32 v215, v154, v158
	global_store_dwordx4 v185, v[212:215], s[76:77]
	v_cvt_pk_bf16_f32 v216, v131, v135
	v_cvt_pk_bf16_f32 v217, v139, v143
	v_cvt_pk_bf16_f32 v218, v147, v151
	v_cvt_pk_bf16_f32 v219, v155, v159
	global_store_dwordx4 v186, v[216:219], s[76:77]
	s_add_u32 s9, s9, 0x800
	s_cmp_lt_u32 s9, 0x2000
	s_cbranch_scc0 .Ltr_done_p0vt
	s_branch .Ltr_st0_p0vt
.Ltr_done_p0vt:
	s_waitcnt lgkmcnt(0)
.LBB0_63:
	v_readlane_b32 s0, v250, 8
	v_readlane_b32 s1, v250, 9
	s_andn2_b64 vcc, exec, s[0:1]
	s_cbranch_vccnz .LBB0_68
	v_mbcnt_lo_u32_b32 v1, -1, 0
	v_mbcnt_hi_u32_b32 v1, -1, v1
	v_and_b32_e32 v2, 64, v1
	v_add_u32_e32 v2, 64, v2
	v_xor_b32_e32 v3, 1, v1
	v_cmp_lt_i32_e64 s[0:1], v3, v2
	v_lshlrev_b32_e32 v0, 2, v220
	v_mov_b32_e32 v33, 0
	v_cndmask_b32_e64 v3, v1, v3, s[0:1]
	v_lshlrev_b32_e32 v36, 2, v3
	v_xor_b32_e32 v3, 2, v1
	v_cmp_lt_i32_e64 s[0:1], v3, v2
	v_cmp_eq_u32_e32 vcc, 0, v220
	v_lshlrev_b32_e32 v32, 2, v0
	v_cndmask_b32_e64 v3, v1, v3, s[0:1]
	v_lshlrev_b32_e32 v37, 2, v3
	v_xor_b32_e32 v3, 4, v1
	v_cmp_lt_i32_e64 s[0:1], v3, v2
	s_movk_i32 s15, 0x1000
	v_mov_b32_e32 v42, 0x358637bd
	v_cndmask_b32_e64 v3, v1, v3, s[0:1]
	v_lshlrev_b32_e32 v38, 2, v3
	v_xor_b32_e32 v3, 8, v1
	v_cmp_lt_i32_e64 s[0:1], v3, v2
	s_waitcnt lgkmcnt(0)
	s_mov_b64 s[16:17], s[96:97]
	v_cndmask_b32_e64 v3, v1, v3, s[0:1]
	v_lshlrev_b32_e32 v39, 2, v3
	v_xor_b32_e32 v3, 16, v1
	v_cmp_lt_i32_e64 s[0:1], v3, v2
	s_nop 1
	v_cndmask_b32_e64 v3, v1, v3, s[0:1]
	v_lshlrev_b32_e32 v40, 2, v3
	v_xor_b32_e32 v3, 32, v1
	v_cmp_lt_i32_e64 s[0:1], v3, v2
	s_nop 1
	v_cndmask_b32_e64 v1, v1, v3, s[0:1]
	s_lshl_b64 s[0:1], s[96:97], 2
	s_add_u32 s0, s68, s0
	s_addc_u32 s1, s69, s1
	s_add_u32 s6, s0, 0x80000
	s_addc_u32 s7, s1, 0
	s_lshl_b64 s[8:9], s[80:81], 2
	s_lshl_b64 s[0:1], s[96:97], 12
	s_add_u32 s0, s30, s0
	s_addc_u32 s1, s31, s1
	v_lshl_add_u64 v[2:3], s[0:1], 0, v[176:177]
	s_mov_b64 s[0:1], 0x4400e00
	v_lshlrev_b32_e32 v41, 2, v1
	v_lshl_add_u64 v[34:35], v[2:3], 0, s[0:1]
	s_lshl_b64 s[10:11], s[80:81], 12
	s_branch .LBB0_66

;     __device__ __forceinline__ void operator()(EPI_ARGS) const {
;         const int pn = u.pn; const bool samp = u.pm >= 64;
;         const int colt = pn * 256 + wc * 32 + 8 * fq;
; #pragma unroll
;         for (int ai = 0; ai < 2; ++ai)
; #pragma unroll
;             for (int m = 0; m < 4; ++m) {
;                 const int row = u.pm * 256 + ai * 128 + wr * 64 + m * 16 + fr;
;                 { const float rs = rstd1[row];
; #pragma unroll
;                   for (int bj = 0; bj < 2; ++bj) { acc[ai][bj][m][0] *= rs; acc[ai][bj][m][1] *= rs; } }
.LBB0_140:
	s_cmp_gt_i32 s8, 63
	s_cselect_b64 s[4:5], -1, 0
	s_cmp_lt_i32 s8, 64
	s_cselect_b64 s[78:79], -1, 0
	s_lshl_b32 s93, s8, 8
	v_readlane_b32 s8, v250, 20
	s_add_i32 s93, s93, s8
	v_or_b32_e32 v154, s93, v143
	v_ashrrev_i32_e32 v155, 31, v154
	v_lshl_add_u64 v[128:129], v[154:155], 2, s[42:43]
	s_add_i32 s32, s93, 0x80
	v_or_b32_e32 v222, s32, v143
	v_mov_b32_e32 v224, v154
	v_ashrrev_i32_e32 v225, 31, v224
	v_lshl_add_u64 v[226:227], v[224:225], 2, s[42:43]
	global_load_dword v204, v[226:227], off
	v_or_b32_e32 v224, 16, v154
	v_ashrrev_i32_e32 v225, 31, v224
	v_lshl_add_u64 v[228:229], v[224:225], 2, s[42:43]
	global_load_dword v206, v[228:229], off
	v_or_b32_e32 v224, 32, v154
	v_ashrrev_i32_e32 v225, 31, v224
	v_lshl_add_u64 v[226:227], v[224:225], 2, s[42:43]
	global_load_dword v208, v[226:227], off
	v_or_b32_e32 v224, 48, v154
	v_ashrrev_i32_e32 v225, 31, v224
	v_lshl_add_u64 v[228:229], v[224:225], 2, s[42:43]
	global_load_dword v210, v[228:229], off
	v_mov_b32_e32 v224, v222
	v_ashrrev_i32_e32 v225, 31, v224
	v_lshl_add_u64 v[226:227], v[224:225], 2, s[42:43]
	global_load_dword v212, v[226:227], off
	v_or_b32_e32 v224, 16, v222
	v_ashrrev_i32_e32 v225, 31, v224
	v_lshl_add_u64 v[228:229], v[224:225], 2, s[42:43]
	global_load_dword v214, v[228:229], off
	v_or_b32_e32 v224, 32, v222
	v_ashrrev_i32_e32 v225, 31, v224
	v_lshl_add_u64 v[226:227], v[224:225], 2, s[42:43]
	global_load_dword v216, v[226:227], off
	v_or_b32_e32 v224, 48, v222
	v_ashrrev_i32_e32 v225, 31, v224
	v_lshl_add_u64 v[228:229], v[224:225], 2, s[42:43]
	global_load_dword v218, v[228:229], off
	s_waitcnt vmcnt(0)
	v_pk_mul_f32 v[126:127], v[126:127], v[204:205] op_sel_hi:[1,0]
	v_pk_mul_f32 v[124:125], v[124:125], v[204:205] op_sel_hi:[1,0]
	v_pk_mul_f32 v[122:123], v[122:123], v[204:205] op_sel_hi:[1,0]
	v_pk_mul_f32 v[120:121], v[120:121], v[204:205] op_sel_hi:[1,0]
	v_pk_mul_f32 v[118:119], v[118:119], v[204:205] op_sel_hi:[1,0]
	v_pk_mul_f32 v[116:117], v[116:117], v[204:205] op_sel_hi:[1,0]
	v_pk_mul_f32 v[114:115], v[114:115], v[204:205] op_sel_hi:[1,0]
	v_pk_mul_f32 v[112:113], v[112:113], v[204:205] op_sel_hi:[1,0]
	v_pk_mul_f32 v[110:111], v[110:111], v[206:207] op_sel_hi:[1,0]
	v_pk_mul_f32 v[108:109], v[108:109], v[206:207] op_sel_hi:[1,0]
	v_pk_mul_f32 v[106:107], v[106:107], v[206:207] op_sel_hi:[1,0]
	v_pk_mul_f32 v[104:105], v[104:105], v[206:207] op_sel_hi:[1,0]
	v_pk_mul_f32 v[102:103], v[102:103], v[206:207] op_sel_hi:[1,0]
	v_pk_mul_f32 v[100:101], v[100:101], v[206:207] op_sel_hi:[1,0]
	v_pk_mul_f32 v[98:99], v[98:99], v[206:207] op_sel_hi:[1,0]
	v_pk_mul_f32 v[96:97], v[96:97], v[206:207] op_sel_hi:[1,0]
	v_pk_mul_f32 v[94:95], v[94:95], v[208:209] op_sel_hi:[1,0]
	v_pk_mul_f32 v[92:93], v[92:93], v[208:209] op_sel_hi:[1,0]
	v_pk_mul_f32 v[90:91], v[90:91], v[208:209] op_sel_hi:[1,0]
	v_pk_mul_f32 v[88:89], v[88:89], v[208:209] op_sel_hi:[1,0]
	v_pk_mul_f32 v[86:87], v[86:87], v[208:209] op_sel_hi:[1,0]
	v_pk_mul_f32 v[84:85], v[84:85], v[208:209] op_sel_hi:[1,0]
	v_pk_mul_f32 v[82:83], v[82:83], v[208:209] op_sel_hi:[1,0]
	v_pk_mul_f32 v[80:81], v[80:81], v[208:209] op_sel_hi:[1,0]
	v_pk_mul_f32 v[78:79], v[78:79], v[210:211] op_sel_hi:[1,0]
	v_pk_mul_f32 v[76:77], v[76:77], v[210:211] op_sel_hi:[1,0]
	v_pk_mul_f32 v[74:75], v[74:75], v[210:211] op_sel_hi:[1,0]
	v_pk_mul_f32 v[72:73], v[72:73], v[210:211] op_sel_hi:[1,0]
	v_pk_mul_f32 v[70:71], v[70:71], v[210:211] op_sel_hi:[1,0]
	v_pk_mul_f32 v[68:69], v[68:69], v[210:211] op_sel_hi:[1,0]
	v_pk_mul_f32 v[66:67], v[66:67], v[210:211] op_sel_hi:[1,0]
	v_pk_mul_f32 v[64:65], v[64:65], v[210:211] op_sel_hi:[1,0]
	v_pk_mul_f32 v[62:63], v[62:63], v[212:213] op_sel_hi:[1,0]
	v_pk_mul_f32 v[60:61], v[60:61], v[212:213] op_sel_hi:[1,0]
	v_pk_mul_f32 v[58:59], v[58:59], v[212:213] op_sel_hi:[1,0]
	v_pk_mul_f32 v[56:57], v[56:57], v[212:213] op_sel_hi:[1,0]
	v_pk_mul_f32 v[54:55], v[54:55], v[212:213] op_sel_hi:[1,0]
	v_pk_mul_f32 v[52:53], v[52:53], v[212:213] op_sel_hi:[1,0]
	v_pk_mul_f32 v[50:51], v[50:51], v[212:213] op_sel_hi:[1,0]
	v_pk_mul_f32 v[48:49], v[48:49], v[212:213] op_sel_hi:[1,0]
	v_pk_mul_f32 v[46:47], v[46:47], v[214:215] op_sel_hi:[1,0]
	v_pk_mul_f32 v[44:45], v[44:45], v[214:215] op_sel_hi:[1,0]
	v_pk_mul_f32 v[42:43], v[42:43], v[214:215] op_sel_hi:[1,0]
	v_pk_mul_f32 v[40:41], v[40:41], v[214:215] op_sel_hi:[1,0]
	v_pk_mul_f32 v[38:39], v[38:39], v[214:215] op_sel_hi:[1,0]
	v_pk_mul_f32 v[36:37], v[36:37], v[214:215] op_sel_hi:[1,0]
	v_pk_mul_f32 v[34:35], v[34:35], v[214:215] op_sel_hi:[1,0]
	v_pk_mul_f32 v[32:33], v[32:33], v[214:215] op_sel_hi:[1,0]
	v_pk_mul_f32 v[30:31], v[30:31], v[216:217] op_sel_hi:[1,0]
	v_pk_mul_f32 v[28:29], v[28:29], v[216:217] op_sel_hi:[1,0]
	v_pk_mul_f32 v[26:27], v[26:27], v[216:217] op_sel_hi:[1,0]
	v_pk_mul_f32 v[24:25], v[24:25], v[216:217] op_sel_hi:[1,0]
	v_pk_mul_f32 v[22:23], v[22:23], v[216:217] op_sel_hi:[1,0]
	v_pk_mul_f32 v[20:21], v[20:21], v[216:217] op_sel_hi:[1,0]
	v_pk_mul_f32 v[18:19], v[18:19], v[216:217] op_sel_hi:[1,0]
	v_pk_mul_f32 v[16:17], v[16:17], v[216:217] op_sel_hi:[1,0]
	v_pk_mul_f32 v[14:15], v[14:15], v[218:219] op_sel_hi:[1,0]
	v_pk_mul_f32 v[12:13], v[12:13], v[218:219] op_sel_hi:[1,0]
	v_pk_mul_f32 v[10:11], v[10:11], v[218:219] op_sel_hi:[1,0]
	v_pk_mul_f32 v[8:9], v[8:9], v[218:219] op_sel_hi:[1,0]
	v_pk_mul_f32 v[6:7], v[6:7], v[218:219] op_sel_hi:[1,0]
	v_pk_mul_f32 v[4:5], v[4:5], v[218:219] op_sel_hi:[1,0]
	v_pk_mul_f32 v[2:3], v[2:3], v[218:219] op_sel_hi:[1,0]
	v_pk_mul_f32 v[0:1], v[0:1], v[218:219] op_sel_hi:[1,0]
	s_lshl_b32 s7, s6, 8
	s_cmp_lt_i32 s6, 24
	s_cselect_b64 s[10:11], -1, 0
	s_cmp_lt_i32 s6, 16
	s_cselect_b64 s[8:9], -1, 0
	s_add_i32 s34, s6, -12
	s_cmp_lt_u32 s34, -4
	s_cselect_b64 s[76:77], -1, 0
	s_and_b32 s73, s6, -4
	s_lshl_b32 s34, s6, 7
	s_ashr_i32 s6, s93, 12
	v_or_b32_e32 v152, s7, v165
	v_add_u32_e32 v175, s7, v169
	s_ashr_i32 s7, s6, 31
	s_lshl_b64 s[66:67], s[6:7], 23
	s_add_i32 s6, s93, 0xffffc000
	s_ashr_i32 s6, s6, 6
	s_ashr_i32 s7, s6, 31
	v_add_u32_e32 v140, s34, v166
	s_and_b32 s95, s93, 0xfc0
	s_lshl_b64 s[90:91], s[6:7], 17
	s_mov_b64 s[84:85], -1
	s_and_b64 vcc, exec, s[10:11]
	v_cndmask_b32_e64 v128, 0, 1, s[8:9]
	v_cmp_ne_u32_e64 s[6:7], 1, v128
	s_cbranch_vccz .LBB0_172
	v_mad_i64_i32 v[156:157], s[8:9], v154, s52, 0
	s_and_b64 vcc, exec, s[6:7]
	s_mov_b64 s[8:9], -1
	s_cbranch_vccnz .LBB0_169
	s_and_b64 vcc, exec, s[76:77]
	s_cbranch_vccz .LBB0_144
	s_movk_i32 s8, 0x800
	v_add_u32_e32 v128, 0xfffffc00, v152
	v_cmp_gt_i32_e32 vcc, s8, v152
	v_lshl_add_u64 v[130:131], s[16:17], 0, v[156:157]
	s_nop 0
	v_cndmask_b32_e32 v128, v128, v152, vcc
	v_ashrrev_i32_e32 v129, 31, v128
	v_lshl_add_u64 v[158:159], v[128:129], 1, v[130:131]
	v_cvt_pk_bf16_f32 v128, v124, v125
	v_cvt_pk_bf16_f32 v129, v126, v127
	v_cvt_pk_bf16_f32 v130, v120, v121
	v_cvt_pk_bf16_f32 v131, v122, v123
	global_store_dwordx4 v[158:159], v[128:131], off

;     __device__ __forceinline__ void operator()(EPI_ARGS) const {
;     ...
;                 const int row = u.pm * 256 + ai * 128 + wr * 64 + m * 16 + fr;
;                 { const float rs = rstd1[row];
; #pragma unroll
;                   for (int bj = 0; bj < 2; ++bj) { acc[ai][bj][m][0] *= rs; acc[ai][bj][m][1] *= rs; } }
.LBB0_174:
	v_or_b32_e32 v116, 16, v154
	v_ashrrev_i32_e32 v117, 31, v116
	v_lshl_add_u64 v[112:113], v[116:117], 2, s[42:43]
	v_cndmask_b32_e64 v113, 0, 1, s[10:11]
	v_cmp_ne_u32_e64 s[8:9], 1, v113
	s_andn2_b64 vcc, exec, s[10:11]
	s_mov_b64 s[10:11], -1
	s_cbranch_vccnz .LBB0_206
	v_mad_i64_i32 v[118:119], s[10:11], v116, s52, 0
	s_and_b64 vcc, exec, s[6:7]
	s_mov_b64 s[10:11], -1
	s_cbranch_vccnz .LBB0_203
	v_cndmask_b32_e64 v112, 0, 1, s[76:77]
	v_cmp_ne_u32_e64 s[10:11], 1, v112
	s_andn2_b64 vcc, exec, s[76:77]
	s_cbranch_vccnz .LBB0_178
	s_movk_i32 s34, 0x800
	v_add_u32_e32 v112, 0xfffffc00, v152
	v_cmp_gt_i32_e32 vcc, s34, v152
	v_lshl_add_u64 v[114:115], s[16:17], 0, v[118:119]
	s_nop 0
	v_cndmask_b32_e32 v112, v112, v152, vcc
	v_ashrrev_i32_e32 v113, 31, v112
	v_lshl_add_u64 v[120:121], v[112:113], 1, v[114:115]
	v_cvt_pk_bf16_f32 v112, v108, v109
	v_cvt_pk_bf16_f32 v113, v110, v111
	v_cvt_pk_bf16_f32 v114, v104, v105
	v_cvt_pk_bf16_f32 v115, v106, v107
	global_store_dwordx4 v[120:121], v[112:115], off

;     __device__ __forceinline__ void operator()(EPI_ARGS) const {
;     ...
;                 const int row = u.pm * 256 + ai * 128 + wr * 64 + m * 16 + fr;
;                 { const float rs = rstd1[row];
; #pragma unroll
;                   for (int bj = 0; bj < 2; ++bj) { acc[ai][bj][m][0] *= rs; acc[ai][bj][m][1] *= rs; } }
.LBB0_208:
	v_or_b32_e32 v100, 32, v154
	v_ashrrev_i32_e32 v101, 31, v100
	v_lshl_add_u64 v[96:97], v[100:101], 2, s[42:43]
	s_and_b64 vcc, exec, s[8:9]
	s_mov_b64 s[10:11], -1
	s_cbranch_vccnz .LBB0_240
	v_mad_i64_i32 v[102:103], s[10:11], v100, s52, 0
	s_and_b64 vcc, exec, s[6:7]
	s_mov_b64 s[10:11], -1
	s_cbranch_vccnz .LBB0_237
	v_cndmask_b32_e64 v96, 0, 1, s[76:77]
	v_cmp_ne_u32_e64 s[10:11], 1, v96
	s_andn2_b64 vcc, exec, s[76:77]
	s_cbranch_vccnz .LBB0_212
	s_movk_i32 s34, 0x800
	v_add_u32_e32 v96, 0xfffffc00, v152
	v_cmp_gt_i32_e32 vcc, s34, v152
	v_lshl_add_u64 v[98:99], s[16:17], 0, v[102:103]
	s_nop 0
	v_cndmask_b32_e32 v96, v96, v152, vcc
	v_ashrrev_i32_e32 v97, 31, v96
	v_lshl_add_u64 v[104:105], v[96:97], 1, v[98:99]
	v_cvt_pk_bf16_f32 v96, v92, v93
	v_cvt_pk_bf16_f32 v97, v94, v95
	v_cvt_pk_bf16_f32 v98, v88, v89
	v_cvt_pk_bf16_f32 v99, v90, v91
	global_store_dwordx4 v[104:105], v[96:99], off

;     __device__ __forceinline__ void operator()(EPI_ARGS) const {
;     ...
;                 const int row = u.pm * 256 + ai * 128 + wr * 64 + m * 16 + fr;
;                 { const float rs = rstd1[row];
; #pragma unroll
;                   for (int bj = 0; bj < 2; ++bj) { acc[ai][bj][m][0] *= rs; acc[ai][bj][m][1] *= rs; } }
.LBB0_242:
	v_or_b32_e32 v84, 48, v154
	v_ashrrev_i32_e32 v85, 31, v84
	v_lshl_add_u64 v[80:81], v[84:85], 2, s[42:43]
	s_and_b64 vcc, exec, s[8:9]
	s_mov_b64 s[10:11], -1
	s_cbranch_vccnz .LBB0_274
	v_mad_i64_i32 v[86:87], s[10:11], v84, s52, 0
	s_and_b64 vcc, exec, s[6:7]
	s_mov_b64 s[10:11], -1
	s_cbranch_vccnz .LBB0_271
	v_cndmask_b32_e64 v80, 0, 1, s[76:77]
	v_cmp_ne_u32_e64 s[10:11], 1, v80
	s_andn2_b64 vcc, exec, s[76:77]
	s_cbranch_vccnz .LBB0_246
	s_movk_i32 s34, 0x800
	v_add_u32_e32 v80, 0xfffffc00, v152
	v_cmp_gt_i32_e32 vcc, s34, v152
	v_lshl_add_u64 v[82:83], s[16:17], 0, v[86:87]
	s_nop 0
	v_cndmask_b32_e32 v80, v80, v152, vcc
	v_ashrrev_i32_e32 v81, 31, v80
	v_lshl_add_u64 v[88:89], v[80:81], 1, v[82:83]
	v_cvt_pk_bf16_f32 v80, v76, v77
	v_cvt_pk_bf16_f32 v81, v78, v79
	v_cvt_pk_bf16_f32 v82, v72, v73
	v_cvt_pk_bf16_f32 v83, v74, v75
	global_store_dwordx4 v[88:89], v[80:83], off

;     __device__ __forceinline__ void operator()(EPI_ARGS) const {
;     ...
;                 const int row = u.pm * 256 + ai * 128 + wr * 64 + m * 16 + fr;
;                 { const float rs = rstd1[row];
; #pragma unroll
;                   for (int bj = 0; bj < 2; ++bj) { acc[ai][bj][m][0] *= rs; acc[ai][bj][m][1] *= rs; } }
.LBB0_276:
	s_add_i32 s11, s93, 0x80
	v_or_b32_e32 v68, s11, v143
	v_ashrrev_i32_e32 v69, 31, v68
	v_lshl_add_u64 v[64:65], v[68:69], 2, s[42:43]
	s_add_i32 s34, s93, 0xffffc080
	s_ashr_i32 s10, s11, 12
	s_ashr_i32 s34, s34, 6
	s_and_b32 s93, s11, 0xfc0
	s_ashr_i32 s11, s10, 31
	s_ashr_i32 s35, s34, 31
	s_and_b64 vcc, exec, s[8:9]
	s_lshl_b64 s[90:91], s[10:11], 23
	s_lshl_b64 s[66:67], s[34:35], 17
	s_mov_b64 s[10:11], -1
	s_cbranch_vccnz .LBB0_308
	v_mad_i64_i32 v[70:71], s[10:11], v68, s52, 0
	s_and_b64 vcc, exec, s[6:7]
	s_mov_b64 s[10:11], -1
	s_cbranch_vccnz .LBB0_305
	v_cndmask_b32_e64 v64, 0, 1, s[76:77]
	v_cmp_ne_u32_e64 s[10:11], 1, v64
	s_andn2_b64 vcc, exec, s[76:77]
	s_cbranch_vccnz .LBB0_280
	s_movk_i32 s34, 0x800
	v_add_u32_e32 v64, 0xfffffc00, v152
	v_cmp_gt_i32_e32 vcc, s34, v152
	v_lshl_add_u64 v[66:67], s[16:17], 0, v[70:71]
	s_nop 0
	v_cndmask_b32_e32 v64, v64, v152, vcc
	v_ashrrev_i32_e32 v65, 31, v64
	v_lshl_add_u64 v[72:73], v[64:65], 1, v[66:67]
	v_cvt_pk_bf16_f32 v64, v60, v61
	v_cvt_pk_bf16_f32 v65, v62, v63
	v_cvt_pk_bf16_f32 v66, v56, v57
	v_cvt_pk_bf16_f32 v67, v58, v59
	global_store_dwordx4 v[72:73], v[64:67], off

;     __device__ __forceinline__ void operator()(EPI_ARGS) const {
;     ...
;                 const int row = u.pm * 256 + ai * 128 + wr * 64 + m * 16 + fr;
;                 { const float rs = rstd1[row];
; #pragma unroll
;                   for (int bj = 0; bj < 2; ++bj) { acc[ai][bj][m][0] *= rs; acc[ai][bj][m][1] *= rs; } }
.LBB0_310:
	v_or_b32_e32 v52, 16, v68
	v_ashrrev_i32_e32 v53, 31, v52
	v_lshl_add_u64 v[48:49], v[52:53], 2, s[42:43]
	s_and_b64 vcc, exec, s[8:9]
	s_mov_b64 s[10:11], -1
	s_cbranch_vccnz .LBB0_342
	v_mad_i64_i32 v[54:55], s[10:11], v52, s52, 0
	s_and_b64 vcc, exec, s[6:7]
	s_mov_b64 s[10:11], -1
	s_cbranch_vccnz .LBB0_339
	v_cndmask_b32_e64 v48, 0, 1, s[76:77]
	v_cmp_ne_u32_e64 s[10:11], 1, v48
	s_andn2_b64 vcc, exec, s[76:77]
	s_cbranch_vccnz .LBB0_314
	s_movk_i32 s34, 0x800
	v_add_u32_e32 v48, 0xfffffc00, v152
	v_cmp_gt_i32_e32 vcc, s34, v152
	v_lshl_add_u64 v[50:51], s[16:17], 0, v[54:55]
	s_nop 0
	v_cndmask_b32_e32 v48, v48, v152, vcc
	v_ashrrev_i32_e32 v49, 31, v48
	v_lshl_add_u64 v[56:57], v[48:49], 1, v[50:51]
	v_cvt_pk_bf16_f32 v48, v44, v45
	v_cvt_pk_bf16_f32 v49, v46, v47
	v_cvt_pk_bf16_f32 v50, v40, v41
	v_cvt_pk_bf16_f32 v51, v42, v43
	global_store_dwordx4 v[56:57], v[48:51], off

;     __device__ __forceinline__ void operator()(EPI_ARGS) const {
;     ...
;                 const int row = u.pm * 256 + ai * 128 + wr * 64 + m * 16 + fr;
;                 { const float rs = rstd1[row];
; #pragma unroll
;                   for (int bj = 0; bj < 2; ++bj) { acc[ai][bj][m][0] *= rs; acc[ai][bj][m][1] *= rs; } }
.LBB0_344:
	v_or_b32_e32 v36, 32, v68
	v_ashrrev_i32_e32 v37, 31, v36
	v_lshl_add_u64 v[32:33], v[36:37], 2, s[42:43]
	s_and_b64 vcc, exec, s[8:9]
	s_mov_b64 s[10:11], -1
	s_cbranch_vccnz .LBB0_376
	v_mad_i64_i32 v[38:39], s[10:11], v36, s52, 0
	s_and_b64 vcc, exec, s[6:7]
	s_mov_b64 s[10:11], -1
	s_cbranch_vccnz .LBB0_373
	v_cndmask_b32_e64 v32, 0, 1, s[76:77]
	v_cmp_ne_u32_e64 s[10:11], 1, v32
	s_andn2_b64 vcc, exec, s[76:77]
	s_cbranch_vccnz .LBB0_348
	s_movk_i32 s34, 0x800
	v_add_u32_e32 v32, 0xfffffc00, v152
	v_cmp_gt_i32_e32 vcc, s34, v152
	v_lshl_add_u64 v[34:35], s[16:17], 0, v[38:39]
	s_nop 0
	v_cndmask_b32_e32 v32, v32, v152, vcc
	v_ashrrev_i32_e32 v33, 31, v32
	v_lshl_add_u64 v[40:41], v[32:33], 1, v[34:35]
	v_cvt_pk_bf16_f32 v32, v28, v29
	v_cvt_pk_bf16_f32 v33, v30, v31
	v_cvt_pk_bf16_f32 v34, v24, v25
	v_cvt_pk_bf16_f32 v35, v26, v27
	global_store_dwordx4 v[40:41], v[32:35], off

;     __device__ __forceinline__ void operator()(EPI_ARGS) const {
;     ...
;                 const int row = u.pm * 256 + ai * 128 + wr * 64 + m * 16 + fr;
;                 { const float rs = rstd1[row];
; #pragma unroll
;                   for (int bj = 0; bj < 2; ++bj) { acc[ai][bj][m][0] *= rs; acc[ai][bj][m][1] *= rs; } }
.LBB0_378:
	v_or_b32_e32 v20, 48, v68
	v_ashrrev_i32_e32 v21, 31, v20
	v_lshl_add_u64 v[16:17], v[20:21], 2, s[42:43]
	s_and_b64 vcc, exec, s[8:9]
	s_mov_b64 s[8:9], -1
	s_cbranch_vccz .LBB0_381
	s_andn2_b64 vcc, exec, s[8:9]
	s_cbranch_vccz .LBB0_412
